# attention: 1+exp as packed adds and self-max removed; seam 0 without per-WG L2 write-back
# baseline (speedup 1.0000x reference)
; #define LAS __attribute__((address_space(3)))
; __global__ void __launch_bounds__(512, 2) hybrid_fwd(Args a) {
;     extern __shared__ __attribute__((aligned(16))) unsigned char lds_raw[];
;     LAS unsigned char* lds = (LAS unsigned char*)lds_raw;
;     const int tid = threadIdx.x, lane = tid & 63, wid = __builtin_amdgcn_readfirstlane(tid >> 6);
;     const int lo = a.ph_lo, hi = a.ph_hi;
_Z10hybrid_fwd4Args:
	s_load_dwordx4 s[44:47], s[0:1], 0x90
	v_mov_b32_e32 v250, 1.0
	v_mov_b32_e32 v251, 1.0
	v_and_b32_e32 v202, 0x3ff, v0
	s_mov_b64 s[84:85], s[0:1]
	s_movk_i32 s0, 0x3ff
	v_readfirstlane_b32 s86, v202
	s_waitcnt lgkmcnt(0)
	s_getreg_b32 s98, hwreg(HW_REG_XCC_ID, 0, 4)
	v_cmp_eq_u32_e32 vcc, 0, v202
	s_and_saveexec_b64 s[4:5], vcc
	s_cbranch_execz .Lcensus_done
	s_add_u32 s6, s44, 0x1400
	s_addc_u32 s7, s45, 0
	s_lshl_b32 s3, s98, 2
	v_mov_b32_e32 v1, s3
	v_mov_b32_e32 v2, 1
	global_atomic_add v1, v1, v2, s[6:7] sc0
	s_waitcnt vmcnt(0)
	v_cmp_eq_u32_e32 vcc, 0, v1
	s_and_b64 exec, exec, vcc
	s_cbranch_execz .Lcensus_done
	v_mov_b32_e32 v1, 0
	global_atomic_add v1, v2, s[6:7] offset:64

; #define LAS __attribute__((address_space(3)))
; __device__ __forceinline__ void attn_unit(LAS unsigned char* lds, const bf16* P, bf16* Y, const float* gq, const float* gk, int b, int h, int qb, int tid, int wid, int lane, ...
;     ...
;                 float kf[8];
; #pragma unroll
;                 for (int i = 0; i < 4; ++i) { kf[2 * i] = blo(kw[hf][i]); kf[2 * i + 1] = bhi(kw[hf][i]); }
;                 float ss = 0.f;
; #pragma unroll
;                 for (int i = 0; i < 8; ++i) ss += kf[i] * kf[i];
;                 ss += __shfl_xor(ss, 1); ss += __shfl_xor(ss, 2); ss += __shfl_xor(ss, 4);
;                 const float rs = __builtin_amdgcn_rsqf(ss * (1.0f / 64.0f) + EPSN);
; #pragma unroll
;                 for (int i = 0; i < 4; ++i) { kf[i] *= rs * gk0[i]; kf[4 + i] *= rs * gk1[i]; }
;                 v4u o; o.x = pk2(kf[0], kf[1]); o.y = pk2(kf[2], kf[3]); o.z = pk2(kf[4], kf[5]); o.w = pk2(kf[6], kf[7]);
;                 *(LAS v4u*)(Ks + (sr + 64 * hf) * 72 + 8 * dc) = o;
; #pragma unroll
;                 for (int i = 0; i < 4; ++i) { Vt[(8 * (dcv + 4 * hf) + 2 * i) * 136 + srv] = (bf16)(vw[hf][i] & 0xffffu); Vt[(8 * (dcv + 4 * hf) + 2 * i + 1) * 136 + srv] = (bf16)(vw[hf][i] >> 16); }
;             }
;         }
;         if (tid == 0) flags[(it + 1) % 3] = 0;
;         LBAR();
;         if (!wdone) {
; #pragma unroll
;             for (int p = 3; p >= 0; --p) {
;                 if (8 * kt + 2 * p <= tg && !wdone) {
;                     float av[2][4];
; #pragma unroll
;                     for (int u = 1; u >= 0; --u) {
;                         const int st = 2 * p + u, sg = 8 * kt + st;
;                         if (sg > tg) {
; #pragma unroll
;                             for (int j = 0; j < 4; ++j) av[u][j] = 0.f;
;                         } else {
;                             const bf16x8 a0 = *(const LAS bf16x8*)(Ks + (16 * st + tq) * 72 + 8 * quad), a1 = *(const LAS bf16x8*)(Ks + (16 * st + tq) * 72 + 32 + 8 * quad);
;                             f32x4 z = (f32x4){0.f, 0.f, 0.f, 0.f};
;                             z = mfma16(a0, Bq0, z); z = mfma16(a1, Bq1, z);
;                             float r[4], be[4];
; #pragma unroll
;                             for (int j = 0; j < 4; ++j) { const float e = fexp2(fminf(z[j], 80.f)); const float rr = frcp(1.0f + e); r[j] = rr; be[j] = e * rr; }
;                             if (sg == tg) {
.LBB0_329:
	v_and_b32_e32 v70, 0xffff0000, v52
	v_lshlrev_b32_e32 v69, 16, v52
	v_mul_f32_e32 v75, v70, v70
	v_lshlrev_b32_e32 v71, 16, v53
	v_fmac_f32_e32 v75, v69, v69
	v_and_b32_e32 v72, 0xffff0000, v53
	v_fmac_f32_e32 v75, v71, v71
	v_lshlrev_b32_e32 v73, 16, v54
	v_fmac_f32_e32 v75, v72, v72
	v_and_b32_e32 v74, 0xffff0000, v54
	v_fmac_f32_e32 v75, v73, v73
	v_and_b32_e32 v52, 0xffff0000, v55
	v_lshlrev_b32_e32 v53, 16, v55
	v_fmac_f32_e32 v75, v74, v74
	v_pk_mul_f32 v[54:55], v[52:53], v[52:53]
	v_lshlrev_b32_e32 v80, 16, v50
	v_add_f32_e32 v55, v55, v75
	v_add_f32_e32 v54, v54, v55
	ds_bpermute_b32 v55, v124, v54
	v_and_b32_e32 v81, 0xffff0000, v50
	v_and_b32_e32 v79, 0xffff0000, v49
	s_waitcnt lgkmcnt(0)
	v_add_f32_e32 v54, v54, v55
	ds_bpermute_b32 v55, v125, v54
	s_waitcnt lgkmcnt(0)
	v_add_f32_e32 v54, v54, v55
	ds_bpermute_b32 v55, v126, v54
	s_waitcnt lgkmcnt(0)
	v_add_f32_e32 v54, v54, v55
	v_fmamk_f32 v54, v54, 0x3c800000, v139
	v_rsq_f32_e32 v75, v54
	s_waitcnt vmcnt(1)
	v_mul_f32_e32 v77, v33, v75
	s_waitcnt vmcnt(0)
	v_mul_f32_e32 v76, v37, v75
	v_mul_f32_e32 v74, v77, v74
	v_and_b32_e32 v77, 0xffff0000, v48
	v_mul_f32_e32 v78, v38, v75
	v_mul_f32_e32 v70, v76, v70
	v_lshlrev_b32_e32 v76, 16, v48
	v_mul_f32_e32 v50, v77, v77
	v_mul_f32_e32 v54, v36, v75
	v_mul_f32_e32 v71, v78, v71
	v_lshlrev_b32_e32 v78, 16, v49
	v_fmac_f32_e32 v50, v76, v76
	v_mul_f32_e32 v69, v54, v69
	v_mul_f32_e32 v54, v34, v75
	v_fmac_f32_e32 v50, v78, v78
	v_mul_f32_e32 v55, v32, v75
	v_mul_f32_e32 v53, v54, v53
	v_mul_f32_e32 v54, v39, v75
	v_fmac_f32_e32 v50, v79, v79
	v_mul_f32_e32 v73, v55, v73
	v_mul_f32_e32 v72, v54, v72
	v_fmac_f32_e32 v50, v80, v80
	v_and_b32_e32 v54, 0xffff0000, v51
	v_lshlrev_b32_e32 v55, 16, v51
	v_fmac_f32_e32 v50, v81, v81
	v_pk_mul_f32 v[48:49], v[54:55], v[54:55]
	s_nop 0
	v_add_f32_e32 v49, v49, v50
	v_add_f32_e32 v50, v48, v49
	ds_bpermute_b32 v51, v124, v50
	v_mul_f32_e32 v48, v35, v75
	v_mul_f32_e32 v52, v48, v52
	v_cvt_pk_bf16_f32 v48, v69, v70
	v_cvt_pk_bf16_f32 v49, v71, v72
	s_waitcnt lgkmcnt(0)
	v_add_f32_e32 v69, v50, v51
	ds_bpermute_b32 v70, v125, v69
	v_cvt_pk_bf16_f32 v50, v73, v74
	v_cvt_pk_bf16_f32 v51, v53, v52
	ds_write_b128 v142, v[48:51]
	ds_write_b16 v127, v44 offset:18432
	ds_write_b16_d16_hi v127, v44 offset:18704
	ds_write_b16 v127, v45 offset:18976
	ds_write_b16_d16_hi v127, v45 offset:19248
	ds_write_b16 v127, v46 offset:19520
	s_waitcnt lgkmcnt(6)
	v_add_f32_e32 v48, v69, v70
	ds_bpermute_b32 v49, v126, v48
	ds_write_b16_d16_hi v127, v46 offset:19792
	ds_write_b16 v127, v47 offset:20064
	ds_write_b16_d16_hi v127, v47 offset:20336
	s_waitcnt lgkmcnt(3)
	v_add_f32_e32 v44, v48, v49
	v_fmamk_f32 v44, v44, 0x3c800000, v139
	v_rsq_f32_e32 v44, v44
	s_nop 0
	v_mul_f32_e32 v45, v36, v44
	v_mul_f32_e32 v46, v32, v44
	v_mul_f32_e32 v47, v37, v44
	v_mul_f32_e32 v45, v45, v76
	v_mul_f32_e32 v46, v46, v80
	v_mul_f32_e32 v47, v47, v77
	v_mul_f32_e32 v48, v33, v44
	v_mul_f32_e32 v49, v38, v44
	v_mul_f32_e32 v50, v34, v44
	v_mul_f32_e32 v51, v39, v44
	v_mul_f32_e32 v44, v35, v44
	v_mul_f32_e32 v48, v48, v81
	v_mul_f32_e32 v49, v49, v78
	v_mul_f32_e32 v50, v50, v55
	v_mul_f32_e32 v51, v51, v79
	v_mul_f32_e32 v52, v44, v54
	v_cvt_pk_bf16_f32 v44, v45, v47
	v_cvt_pk_bf16_f32 v45, v49, v51
	v_cvt_pk_bf16_f32 v46, v46, v48
	v_cvt_pk_bf16_f32 v47, v50, v52
	ds_write_b128 v142, v[44:47] offset:9216
	ds_write_b16 v127, v40 offset:27136
	ds_write_b16_d16_hi v127, v40 offset:27408
	ds_write_b16 v127, v41 offset:27680
	ds_write_b16_d16_hi v127, v41 offset:27952
	ds_write_b16 v127, v42 offset:28224
	ds_write_b16_d16_hi v127, v42 offset:28496
	ds_write_b16 v127, v43 offset:28768
	ds_write_b16_d16_hi v127, v43 offset:29040
	s_mov_b64 s[10:11], exec
	v_readlane_b32 s12, v249, 28
	v_readlane_b32 s13, v249, 29
	s_and_b64 s[12:13], s[10:11], s[12:13]
	s_mov_b64 exec, s[12:13]
	ds_write_b32 v95, v95 offset:35844
	s_or_b64 exec, exec, s[10:11]
	s_waitcnt lgkmcnt(0)
	s_barrier
	s_andn2_b64 vcc, exec, s[0:1]
	s_cbranch_vccnz .LBB0_342
	s_andn2_b64 vcc, exec, s[18:19]
	s_cbranch_vccnz .LBB0_343
	ds_read_b128 v[40:43], v134
	ds_read_b128 v[44:47], v134 offset:64
	s_andn2_b64 vcc, exec, s[20:21]
	s_waitcnt lgkmcnt(1)
	v_mfma_f32_16x16x32_bf16 v[40:43], v[40:43], v[24:27], 0
	s_waitcnt lgkmcnt(0)
	v_mfma_f32_16x16x32_bf16 v[40:43], v[44:47], v[28:31], v[40:43]
	s_nop 7
	v_min_f32_e32 v40, 0x42a00000, v40
	v_min_f32_e32 v41, 0x42a00000, v41
	v_min_f32_e32 v42, 0x42a00000, v42
	v_min_f32_e32 v43, 0x42a00000, v43
	v_exp_f32_e32 v40, v40
	v_exp_f32_e32 v41, v41
	v_exp_f32_e32 v46, v42
	v_exp_f32_e32 v47, v43
	v_pk_add_f32 v[42:43], v[40:41], v[250:251]
	v_pk_add_f32 v[44:45], v[46:47], v[250:251]
	v_rcp_f32_e32 v48, v42
	v_rcp_f32_e32 v49, v43
	v_rcp_f32_e32 v44, v44
	v_rcp_f32_e32 v45, v45
	v_pk_mul_f32 v[42:43], v[40:41], v[48:49]
	v_pk_mul_f32 v[40:41], v[46:47], v[44:45]
	s_cbranch_vccnz .LBB0_335
	v_mov_b32_e32 v46, v93
	s_nop 0
	v_cmp_lt_i32_e64 s[12:13], v129, v46
	v_cmp_lt_i32_e64 s[14:15], v130, v46
	v_cmp_lt_i32_e64 s[10:11], v128, v46
	s_or_b64 s[12:13], s[14:15], s[12:13]
	v_cmp_lt_i32_e32 vcc, v98, v46
	s_or_b64 s[10:11], s[12:13], s[10:11]
	s_or_b64 vcc, s[10:11], vcc
	v_cndmask_b32_e64 v41, 0, v41, s[14:15]
	v_cndmask_b32_e64 v40, 0, v40, s[12:13]
	v_cndmask_b32_e64 v43, 0, v43, s[10:11]
	v_cndmask_b32_e32 v42, 0, v42, vcc
	v_cndmask_b32_e64 v44, 1.0, v44, s[12:13]
	v_cndmask_b32_e64 v49, 1.0, v49, s[10:11]
	v_cndmask_b32_e32 v48, 1.0, v48, vcc
	v_cndmask_b32_e64 v45, 1.0, v45, s[14:15]

; #define LAS __attribute__((address_space(3)))
; __device__ __forceinline__ float fexp2(float x) { return __builtin_amdgcn_exp2f(x); }
; __device__ __forceinline__ float frcp(float x) { return __builtin_amdgcn_rcpf(x); }
; __device__ __forceinline__ f32x4 mfma16(bf16x8 a, bf16x8 b, f32x4 c) { return __builtin_amdgcn_mfma_f32_16x16x32_bf16(a, b, c, 0, 0, 0); }
; __device__ __forceinline__ void attn_unit(LAS unsigned char* lds, const bf16* P, bf16* Y, const float* gq, const float* gk, int b, int h, int qb, int tid, int wid, int lane, ...
;     ...
;                             const bf16x8 a0 = *(const LAS bf16x8*)(Ks + (16 * st + tq) * 72 + 8 * quad), a1 = *(const LAS bf16x8*)(Ks + (16 * st + tq) * 72 + 32 + 8 * quad);
;                             f32x4 z = (f32x4){0.f, 0.f, 0.f, 0.f};
;                             z = mfma16(a0, Bq0, z); z = mfma16(a1, Bq1, z);
;                             float r[4], be[4];
; #pragma unroll
;                             for (int j = 0; j < 4; ++j) { const float e = fexp2(fminf(z[j], 80.f)); const float rr = frcp(1.0f + e); r[j] = rr; be[j] = e * rr; }
;                             if (sg == tg) {
;                                 int tql = tq; asm volatile("" : "+v"(tql));
; #pragma unroll
;                                 for (int j = 0; j < 4; ++j) if (4 * quad + j >= tql) { r[j] = 1.0f; be[j] = 0.f; }
.LBB0_344:
	ds_read_b128 v[44:47], v136 offset:13824
	ds_read_b128 v[48:51], v136 offset:13888
	s_andn2_b64 vcc, exec, s[16:17]
	s_waitcnt lgkmcnt(1)
	v_mfma_f32_16x16x32_bf16 v[44:47], v[44:47], v[24:27], 0
	s_waitcnt lgkmcnt(0)
	v_mfma_f32_16x16x32_bf16 v[44:47], v[48:51], v[28:31], v[44:47]
	s_nop 7
	v_min_f32_e32 v44, 0x42a00000, v44
	v_min_f32_e32 v45, 0x42a00000, v45
	v_min_f32_e32 v48, 0x42a00000, v46
	v_min_f32_e32 v49, 0x42a00000, v47
	v_exp_f32_e32 v46, v44
	v_exp_f32_e32 v47, v45
	v_exp_f32_e32 v52, v48
	v_exp_f32_e32 v53, v49
	v_pk_add_f32 v[44:45], v[46:47], v[250:251]
	v_pk_add_f32 v[48:49], v[52:53], v[250:251]
	v_rcp_f32_e32 v50, v44
	v_rcp_f32_e32 v51, v45
	v_rcp_f32_e32 v44, v48
	v_rcp_f32_e32 v45, v49
	v_pk_mul_f32 v[48:49], v[46:47], v[50:51]
	v_pk_mul_f32 v[46:47], v[52:53], v[44:45]
	s_cbranch_vccnz .LBB0_346
	v_mov_b32_e32 v52, v93
	s_nop 0
	v_cmp_lt_i32_e64 s[12:13], v129, v52
	v_cmp_lt_i32_e64 s[14:15], v130, v52
	v_cmp_lt_i32_e64 s[10:11], v128, v52
	s_or_b64 s[12:13], s[14:15], s[12:13]
	v_cmp_lt_i32_e32 vcc, v98, v52
	s_or_b64 s[10:11], s[12:13], s[10:11]
	s_or_b64 vcc, s[10:11], vcc
	v_cndmask_b32_e64 v47, 0, v47, s[14:15]
	v_cndmask_b32_e64 v46, 0, v46, s[12:13]
	v_cndmask_b32_e64 v49, 0, v49, s[10:11]
	v_cndmask_b32_e32 v48, 0, v48, vcc
	v_cndmask_b32_e64 v44, 1.0, v44, s[12:13]
	v_cndmask_b32_e64 v51, 1.0, v51, s[10:11]
	v_cndmask_b32_e32 v50, 1.0, v50, vcc
	v_cndmask_b32_e64 v45, 1.0, v45, s[14:15]

; #define LAS __attribute__((address_space(3)))
; __device__ __forceinline__ float fexp2(float x) { return __builtin_amdgcn_exp2f(x); }
; __device__ __forceinline__ float frcp(float x) { return __builtin_amdgcn_rcpf(x); }
; __device__ __forceinline__ f32x4 mfma16(bf16x8 a, bf16x8 b, f32x4 c) { return __builtin_amdgcn_mfma_f32_16x16x32_bf16(a, b, c, 0, 0, 0); }
; #define LBAR() do { asm volatile("s_waitcnt lgkmcnt(0)" ::: "memory"); __builtin_amdgcn_s_barrier(); asm volatile("" ::: "memory"); } while (0)
; __device__ __forceinline__ void attn_unit(LAS unsigned char* lds, const bf16* P, bf16* Y, const float* gq, const float* gk, int b, int h, int qb, int tid, int wid, int lane, ...
;     ...
;         if (tid == 0) flags[(it + 1) % 3] = 0;
;         LBAR();
;         if (!wdone) {
; #pragma unroll
;             for (int p = 3; p >= 0; --p) {
;                 if (8 * kt + 2 * p <= tg && !wdone) {
;                     float av[2][4];
; #pragma unroll
;                     for (int u = 1; u >= 0; --u) {
;                         const int st = 2 * p + u, sg = 8 * kt + st;
;                         if (sg > tg) {
; #pragma unroll
;                             for (int j = 0; j < 4; ++j) av[u][j] = 0.f;
;                         } else {
;                             const bf16x8 a0 = *(const LAS bf16x8*)(Ks + (16 * st + tq) * 72 + 8 * quad), a1 = *(const LAS bf16x8*)(Ks + (16 * st + tq) * 72 + 32 + 8 * quad);
;                             f32x4 z = (f32x4){0.f, 0.f, 0.f, 0.f};
;                             z = mfma16(a0, Bq0, z); z = mfma16(a1, Bq1, z);
;                             float r[4], be[4];
; #pragma unroll
;                             for (int j = 0; j < 4; ++j) { const float e = fexp2(fminf(z[j], 80.f)); const float rr = frcp(1.0f + e); r[j] = rr; be[j] = e * rr; }
;                             if (sg == tg) {
;                                 int tql = tq; asm volatile("" : "+v"(tql));
; #pragma unroll
;                                 for (int j = 0; j < 4; ++j) if (4 * quad + j >= tql) { r[j] = 1.0f; be[j] = 0.f; }
.LBB0_385:
	s_or_b64 exec, exec, s[12:13]
	s_xor_b64 s[12:13], s[10:11], -1
	s_mul_hi_u32 s10, s71, 0xaaaaaaab
	s_waitcnt lgkmcnt(0)
	s_barrier
	s_lshr_b32 s81, s10, 1
	s_mul_i32 s81, s81, -12
	s_mov_b64 s[10:11], -1
	s_and_saveexec_b64 s[64:65], s[12:13]
	s_cbranch_execz .LBB0_473
	s_add_i32 s82, s37, s78
	s_add_i32 s10, s82, 0x76
	s_cmp_gt_u32 s10, s36
	s_mov_b64 s[10:11], 0
	s_cbranch_scc1 .LBB0_407
	s_add_i32 s10, s82, 0x77
	s_cmp_gt_u32 s10, s36
	v_mov_b32_e32 v59, 0
	s_cbranch_scc1 .LBB0_397
	ds_read_b128 v[56:59], v134
	ds_read_b128 v[60:63], v134 offset:64
	s_cmp_lg_u32 s50, s78
	s_waitcnt lgkmcnt(1)
	v_mfma_f32_16x16x32_bf16 v[56:59], v[56:59], v[24:27], 0
	s_waitcnt lgkmcnt(0)
	v_mfma_f32_16x16x32_bf16 v[56:59], v[60:63], v[28:31], v[56:59]
	s_nop 7
	v_min_f32_e32 v56, 0x42a00000, v56
	v_min_f32_e32 v57, 0x42a00000, v57
	v_min_f32_e32 v60, 0x42a00000, v58
	v_min_f32_e32 v61, 0x42a00000, v59
	v_exp_f32_e32 v58, v56
	v_exp_f32_e32 v59, v57
	v_exp_f32_e32 v60, v60
	v_exp_f32_e32 v61, v61
	v_pk_add_f32 v[56:57], v[58:59], v[250:251]
	v_pk_add_f32 v[64:65], v[60:61], v[250:251]
	v_rcp_f32_e32 v62, v56
	v_rcp_f32_e32 v63, v57
	v_rcp_f32_e32 v56, v64
	v_rcp_f32_e32 v57, v65
	v_pk_mul_f32 v[58:59], v[58:59], v[62:63]
	v_pk_mul_f32 v[60:61], v[60:61], v[56:57]
	s_cbranch_scc1 .LBB0_390
	v_mov_b32_e32 v64, v93
	s_nop 0
	v_cmp_lt_i32_e64 s[12:13], v129, v64
	v_cmp_lt_i32_e64 s[14:15], v130, v64
	v_cmp_lt_i32_e64 s[10:11], v128, v64
	s_or_b64 s[12:13], s[14:15], s[12:13]
	v_cmp_lt_i32_e32 vcc, v98, v64
	s_or_b64 s[10:11], s[12:13], s[10:11]
	s_or_b64 vcc, s[10:11], vcc
	v_cndmask_b32_e64 v61, 0, v61, s[14:15]
	v_cndmask_b32_e64 v60, 0, v60, s[12:13]
	v_cndmask_b32_e64 v59, 0, v59, s[10:11]
	v_cndmask_b32_e32 v58, 0, v58, vcc
	v_cndmask_b32_e64 v56, 1.0, v56, s[12:13]
	v_cndmask_b32_e64 v63, 1.0, v63, s[10:11]
	v_cndmask_b32_e32 v62, 1.0, v62, vcc
	v_cndmask_b32_e64 v57, 1.0, v57, s[14:15]

; #define LAS __attribute__((address_space(3)))
; __device__ __forceinline__ float fexp2(float x) { return __builtin_amdgcn_exp2f(x); }
; __device__ __forceinline__ float frcp(float x) { return __builtin_amdgcn_rcpf(x); }
; __device__ __forceinline__ f32x4 mfma16(bf16x8 a, bf16x8 b, f32x4 c) { return __builtin_amdgcn_mfma_f32_16x16x32_bf16(a, b, c, 0, 0, 0); }
; __device__ __forceinline__ void attn_unit(LAS unsigned char* lds, const bf16* P, bf16* Y, const float* gq, const float* gk, int b, int h, int qb, int tid, int wid, int lane, ...
;     ...
;                         const int st = 2 * p + u, sg = 8 * kt + st;
;                         if (sg > tg) {
; #pragma unroll
;                             for (int j = 0; j < 4; ++j) av[u][j] = 0.f;
;                         } else {
;                             const bf16x8 a0 = *(const LAS bf16x8*)(Ks + (16 * st + tq) * 72 + 8 * quad), a1 = *(const LAS bf16x8*)(Ks + (16 * st + tq) * 72 + 32 + 8 * quad);
;                             f32x4 z = (f32x4){0.f, 0.f, 0.f, 0.f};
;                             z = mfma16(a0, Bq0, z); z = mfma16(a1, Bq1, z);
;                             float r[4], be[4];
; #pragma unroll
;                             for (int j = 0; j < 4; ++j) { const float e = fexp2(fminf(z[j], 80.f)); const float rr = frcp(1.0f + e); r[j] = rr; be[j] = e * rr; }
;                             if (sg == tg) {
;                                 int tql = tq; asm volatile("" : "+v"(tql));
; #pragma unroll
;                                 for (int j = 0; j < 4; ++j) if (4 * quad + j >= tql) { r[j] = 1.0f; be[j] = 0.f; }
.LBB0_398:
	ds_read_b128 v[60:63], v136 offset:13824
	ds_read_b128 v[64:67], v136 offset:13888
	s_cmp_lg_u32 s51, s78
	s_waitcnt lgkmcnt(1)
	v_mfma_f32_16x16x32_bf16 v[60:63], v[60:63], v[24:27], 0
	s_waitcnt lgkmcnt(0)
	v_mfma_f32_16x16x32_bf16 v[60:63], v[64:67], v[28:31], v[60:63]
	s_nop 7
	v_min_f32_e32 v60, 0x42a00000, v60
	v_min_f32_e32 v61, 0x42a00000, v61
	v_min_f32_e32 v64, 0x42a00000, v62
	v_min_f32_e32 v65, 0x42a00000, v63
	v_exp_f32_e32 v62, v60
	v_exp_f32_e32 v63, v61
	v_exp_f32_e32 v84, v64
	v_exp_f32_e32 v85, v65
	v_pk_add_f32 v[60:61], v[62:63], v[250:251]
	v_pk_add_f32 v[64:65], v[84:85], v[250:251]
	v_rcp_f32_e32 v66, v60
	v_rcp_f32_e32 v67, v61
	v_rcp_f32_e32 v60, v64
	v_rcp_f32_e32 v61, v65
	v_pk_mul_f32 v[64:65], v[62:63], v[66:67]
	v_pk_mul_f32 v[62:63], v[84:85], v[60:61]
	s_cbranch_scc1 .LBB0_400
	v_mov_b32_e32 v84, v93
	s_nop 0
	v_cmp_lt_i32_e64 s[12:13], v129, v84
	v_cmp_lt_i32_e64 s[14:15], v130, v84
	v_cmp_lt_i32_e64 s[10:11], v128, v84
	s_or_b64 s[12:13], s[14:15], s[12:13]
	v_cmp_lt_i32_e32 vcc, v98, v84
	s_or_b64 s[10:11], s[12:13], s[10:11]
	s_or_b64 vcc, s[10:11], vcc
	v_cndmask_b32_e64 v63, 0, v63, s[14:15]
	v_cndmask_b32_e64 v62, 0, v62, s[12:13]
	v_cndmask_b32_e64 v65, 0, v65, s[10:11]
	v_cndmask_b32_e32 v64, 0, v64, vcc
	v_cndmask_b32_e64 v60, 1.0, v60, s[12:13]
	v_cndmask_b32_e64 v67, 1.0, v67, s[10:11]
	v_cndmask_b32_e32 v66, 1.0, v66, vcc
	v_cndmask_b32_e64 v61, 1.0, v61, s[14:15]

; #define LAS __attribute__((address_space(3)))
; __device__ __forceinline__ float fexp2(float x) { return __builtin_amdgcn_exp2f(x); }
; __device__ __forceinline__ float frcp(float x) { return __builtin_amdgcn_rcpf(x); }
; __device__ __forceinline__ f32x4 mfma16(bf16x8 a, bf16x8 b, f32x4 c) { return __builtin_amdgcn_mfma_f32_16x16x32_bf16(a, b, c, 0, 0, 0); }
; __device__ __forceinline__ void attn_unit(LAS unsigned char* lds, const bf16* P, bf16* Y, const float* gq, const float* gk, int b, int h, int qb, int tid, int wid, int lane, ...
;     ...
;                         const int st = 2 * p + u, sg = 8 * kt + st;
;                         if (sg > tg) {
; #pragma unroll
;                             for (int j = 0; j < 4; ++j) av[u][j] = 0.f;
;                         } else {
;                             const bf16x8 a0 = *(const LAS bf16x8*)(Ks + (16 * st + tq) * 72 + 8 * quad), a1 = *(const LAS bf16x8*)(Ks + (16 * st + tq) * 72 + 32 + 8 * quad);
;                             f32x4 z = (f32x4){0.f, 0.f, 0.f, 0.f};
;                             z = mfma16(a0, Bq0, z); z = mfma16(a1, Bq1, z);
;                             float r[4], be[4];
; #pragma unroll
;                             for (int j = 0; j < 4; ++j) { const float e = fexp2(fminf(z[j], 80.f)); const float rr = frcp(1.0f + e); r[j] = rr; be[j] = e * rr; }
;                             if (sg == tg) {
;                                 int tql = tq; asm volatile("" : "+v"(tql));
; #pragma unroll
;                                 for (int j = 0; j < 4; ++j) if (4 * quad + j >= tql) { r[j] = 1.0f; be[j] = 0.f; }
.LBB0_407:
	s_add_i32 s12, s82, 0x74
	s_cmp_gt_u32 s12, s36
	s_cselect_b64 s[12:13], -1, 0
	s_or_b64 s[12:13], s[12:13], s[10:11]
	s_and_b64 vcc, exec, s[12:13]
	s_cbranch_vccnz .LBB0_428
	s_add_i32 s10, s82, 0x75
	s_cmp_gt_u32 s10, s36
	v_mov_b32_e32 v59, 0
	s_cbranch_scc1 .LBB0_418
	ds_read_b128 v[56:59], v136 offset:11520
	ds_read_b128 v[60:63], v136 offset:11584
	s_cmp_lg_u32 s48, s78
	s_waitcnt lgkmcnt(1)
	v_mfma_f32_16x16x32_bf16 v[56:59], v[56:59], v[24:27], 0
	s_waitcnt lgkmcnt(0)
	v_mfma_f32_16x16x32_bf16 v[56:59], v[60:63], v[28:31], v[56:59]
	s_nop 7
	v_min_f32_e32 v56, 0x42a00000, v56
	v_min_f32_e32 v57, 0x42a00000, v57
	v_min_f32_e32 v60, 0x42a00000, v58
	v_min_f32_e32 v61, 0x42a00000, v59
	v_exp_f32_e32 v58, v56
	v_exp_f32_e32 v59, v57
	v_exp_f32_e32 v60, v60
	v_exp_f32_e32 v61, v61
	v_pk_add_f32 v[56:57], v[58:59], v[250:251]
	v_pk_add_f32 v[64:65], v[60:61], v[250:251]
	v_rcp_f32_e32 v62, v56
	v_rcp_f32_e32 v63, v57
	v_rcp_f32_e32 v56, v64
	v_rcp_f32_e32 v57, v65
	v_pk_mul_f32 v[58:59], v[58:59], v[62:63]
	v_pk_mul_f32 v[60:61], v[60:61], v[56:57]
	s_cbranch_scc1 .LBB0_411
	v_mov_b32_e32 v64, v93
	s_nop 0
	v_cmp_lt_i32_e64 s[12:13], v129, v64
	v_cmp_lt_i32_e64 s[14:15], v130, v64
	v_cmp_lt_i32_e64 s[10:11], v128, v64
	s_or_b64 s[12:13], s[14:15], s[12:13]
	v_cmp_lt_i32_e32 vcc, v98, v64
	s_or_b64 s[10:11], s[12:13], s[10:11]
	s_or_b64 vcc, s[10:11], vcc
	v_cndmask_b32_e64 v61, 0, v61, s[14:15]
	v_cndmask_b32_e64 v60, 0, v60, s[12:13]
	v_cndmask_b32_e64 v59, 0, v59, s[10:11]
	v_cndmask_b32_e32 v58, 0, v58, vcc
	v_cndmask_b32_e64 v56, 1.0, v56, s[12:13]
	v_cndmask_b32_e64 v63, 1.0, v63, s[10:11]
	v_cndmask_b32_e32 v62, 1.0, v62, vcc
	v_cndmask_b32_e64 v57, 1.0, v57, s[14:15]

; #define LAS __attribute__((address_space(3)))
; __device__ __forceinline__ float fexp2(float x) { return __builtin_amdgcn_exp2f(x); }
; __device__ __forceinline__ float frcp(float x) { return __builtin_amdgcn_rcpf(x); }
; __device__ __forceinline__ f32x4 mfma16(bf16x8 a, bf16x8 b, f32x4 c) { return __builtin_amdgcn_mfma_f32_16x16x32_bf16(a, b, c, 0, 0, 0); }
; __device__ __forceinline__ void attn_unit(LAS unsigned char* lds, const bf16* P, bf16* Y, const float* gq, const float* gk, int b, int h, int qb, int tid, int wid, int lane, ...
;     ...
;                         const int st = 2 * p + u, sg = 8 * kt + st;
;                         if (sg > tg) {
; #pragma unroll
;                             for (int j = 0; j < 4; ++j) av[u][j] = 0.f;
;                         } else {
;                             const bf16x8 a0 = *(const LAS bf16x8*)(Ks + (16 * st + tq) * 72 + 8 * quad), a1 = *(const LAS bf16x8*)(Ks + (16 * st + tq) * 72 + 32 + 8 * quad);
;                             f32x4 z = (f32x4){0.f, 0.f, 0.f, 0.f};
;                             z = mfma16(a0, Bq0, z); z = mfma16(a1, Bq1, z);
;                             float r[4], be[4];
; #pragma unroll
;                             for (int j = 0; j < 4; ++j) { const float e = fexp2(fminf(z[j], 80.f)); const float rr = frcp(1.0f + e); r[j] = rr; be[j] = e * rr; }
;                             if (sg == tg) {
;                                 int tql = tq; asm volatile("" : "+v"(tql));
; #pragma unroll
;                                 for (int j = 0; j < 4; ++j) if (4 * quad + j >= tql) { r[j] = 1.0f; be[j] = 0.f; }
.LBB0_419:
	ds_read_b128 v[60:63], v136 offset:9216
	ds_read_b128 v[64:67], v136 offset:9280
	s_cmp_lg_u32 s49, s78
	s_waitcnt lgkmcnt(1)
	v_mfma_f32_16x16x32_bf16 v[60:63], v[60:63], v[24:27], 0
	s_waitcnt lgkmcnt(0)
	v_mfma_f32_16x16x32_bf16 v[60:63], v[64:67], v[28:31], v[60:63]
	s_nop 7
	v_min_f32_e32 v60, 0x42a00000, v60
	v_min_f32_e32 v61, 0x42a00000, v61
	v_min_f32_e32 v64, 0x42a00000, v62
	v_min_f32_e32 v65, 0x42a00000, v63
	v_exp_f32_e32 v62, v60
	v_exp_f32_e32 v63, v61
	v_exp_f32_e32 v84, v64
	v_exp_f32_e32 v85, v65
	v_pk_add_f32 v[60:61], v[62:63], v[250:251]
	v_pk_add_f32 v[64:65], v[84:85], v[250:251]
	v_rcp_f32_e32 v66, v60
	v_rcp_f32_e32 v67, v61
	v_rcp_f32_e32 v60, v64
	v_rcp_f32_e32 v61, v65
	v_pk_mul_f32 v[64:65], v[62:63], v[66:67]
	v_pk_mul_f32 v[62:63], v[84:85], v[60:61]
	s_cbranch_scc1 .LBB0_421
	v_mov_b32_e32 v84, v93
	s_nop 0
	v_cmp_lt_i32_e64 s[12:13], v129, v84
	v_cmp_lt_i32_e64 s[14:15], v130, v84
	v_cmp_lt_i32_e64 s[10:11], v128, v84
	s_or_b64 s[12:13], s[14:15], s[12:13]
	v_cmp_lt_i32_e32 vcc, v98, v84
	s_or_b64 s[10:11], s[12:13], s[10:11]
	s_or_b64 vcc, s[10:11], vcc
	v_cndmask_b32_e64 v63, 0, v63, s[14:15]
	v_cndmask_b32_e64 v62, 0, v62, s[12:13]
	v_cndmask_b32_e64 v65, 0, v65, s[10:11]
	v_cndmask_b32_e32 v64, 0, v64, vcc
	v_cndmask_b32_e64 v60, 1.0, v60, s[12:13]
	v_cndmask_b32_e64 v67, 1.0, v67, s[10:11]
	v_cndmask_b32_e32 v66, 1.0, v66, vcc
	v_cndmask_b32_e64 v61, 1.0, v61, s[14:15]

; #define LAS __attribute__((address_space(3)))
; __device__ __forceinline__ float fexp2(float x) { return __builtin_amdgcn_exp2f(x); }
; __device__ __forceinline__ float frcp(float x) { return __builtin_amdgcn_rcpf(x); }
; __device__ __forceinline__ f32x4 mfma16(bf16x8 a, bf16x8 b, f32x4 c) { return __builtin_amdgcn_mfma_f32_16x16x32_bf16(a, b, c, 0, 0, 0); }
; __device__ __forceinline__ void attn_unit(LAS unsigned char* lds, const bf16* P, bf16* Y, const float* gq, const float* gk, int b, int h, int qb, int tid, int wid, int lane, ...
;     ...
;                         const int st = 2 * p + u, sg = 8 * kt + st;
;                         if (sg > tg) {
; #pragma unroll
;                             for (int j = 0; j < 4; ++j) av[u][j] = 0.f;
;                         } else {
;                             const bf16x8 a0 = *(const LAS bf16x8*)(Ks + (16 * st + tq) * 72 + 8 * quad), a1 = *(const LAS bf16x8*)(Ks + (16 * st + tq) * 72 + 32 + 8 * quad);
;                             f32x4 z = (f32x4){0.f, 0.f, 0.f, 0.f};
;                             z = mfma16(a0, Bq0, z); z = mfma16(a1, Bq1, z);
;                             float r[4], be[4];
; #pragma unroll
;                             for (int j = 0; j < 4; ++j) { const float e = fexp2(fminf(z[j], 80.f)); const float rr = frcp(1.0f + e); r[j] = rr; be[j] = e * rr; }
;                             if (sg == tg) {
;                                 int tql = tq; asm volatile("" : "+v"(tql));
; #pragma unroll
;                                 for (int j = 0; j < 4; ++j) if (4 * quad + j >= tql) { r[j] = 1.0f; be[j] = 0.f; }
.LBB0_428:
	s_add_i32 s12, s82, 0x72
	s_cmp_gt_u32 s12, s36
	s_cselect_b64 s[12:13], -1, 0
	s_or_b64 s[12:13], s[12:13], s[10:11]
	s_and_b64 vcc, exec, s[12:13]
	s_cbranch_vccnz .LBB0_449
	s_add_i32 s10, s82, 0x73
	s_cmp_gt_u32 s10, s36
	v_mov_b32_e32 v59, 0
	s_cbranch_scc1 .LBB0_439
	ds_read_b128 v[56:59], v137
	ds_read_b128 v[60:63], v137 offset:64
	s_cmp_lg_u32 s40, s78
	s_waitcnt lgkmcnt(1)
	v_mfma_f32_16x16x32_bf16 v[56:59], v[56:59], v[24:27], 0
	s_waitcnt lgkmcnt(0)
	v_mfma_f32_16x16x32_bf16 v[56:59], v[60:63], v[28:31], v[56:59]
	s_nop 7
	v_min_f32_e32 v56, 0x42a00000, v56
	v_min_f32_e32 v57, 0x42a00000, v57
	v_min_f32_e32 v60, 0x42a00000, v58
	v_min_f32_e32 v61, 0x42a00000, v59
	v_exp_f32_e32 v58, v56
	v_exp_f32_e32 v59, v57
	v_exp_f32_e32 v60, v60
	v_exp_f32_e32 v61, v61
	v_pk_add_f32 v[56:57], v[58:59], v[250:251]
	v_pk_add_f32 v[64:65], v[60:61], v[250:251]
	v_rcp_f32_e32 v62, v56
	v_rcp_f32_e32 v63, v57
	v_rcp_f32_e32 v56, v64
	v_rcp_f32_e32 v57, v65
	v_pk_mul_f32 v[58:59], v[58:59], v[62:63]
	v_pk_mul_f32 v[60:61], v[60:61], v[56:57]
	s_cbranch_scc1 .LBB0_432
	v_mov_b32_e32 v64, v93
	s_nop 0
	v_cmp_lt_i32_e64 s[12:13], v129, v64
	v_cmp_lt_i32_e64 s[14:15], v130, v64
	v_cmp_lt_i32_e64 s[10:11], v128, v64
	s_or_b64 s[12:13], s[14:15], s[12:13]
	v_cmp_lt_i32_e32 vcc, v98, v64
	s_or_b64 s[10:11], s[12:13], s[10:11]
	s_or_b64 vcc, s[10:11], vcc
	v_cndmask_b32_e64 v61, 0, v61, s[14:15]
	v_cndmask_b32_e64 v60, 0, v60, s[12:13]
	v_cndmask_b32_e64 v59, 0, v59, s[10:11]
	v_cndmask_b32_e32 v58, 0, v58, vcc
	v_cndmask_b32_e64 v56, 1.0, v56, s[12:13]
	v_cndmask_b32_e64 v63, 1.0, v63, s[10:11]
	v_cndmask_b32_e32 v62, 1.0, v62, vcc
	v_cndmask_b32_e64 v57, 1.0, v57, s[14:15]

; #define LAS __attribute__((address_space(3)))
; __device__ __forceinline__ float fexp2(float x) { return __builtin_amdgcn_exp2f(x); }
; __device__ __forceinline__ float frcp(float x) { return __builtin_amdgcn_rcpf(x); }
; __device__ __forceinline__ f32x4 mfma16(bf16x8 a, bf16x8 b, f32x4 c) { return __builtin_amdgcn_mfma_f32_16x16x32_bf16(a, b, c, 0, 0, 0); }
; __device__ __forceinline__ void attn_unit(LAS unsigned char* lds, const bf16* P, bf16* Y, const float* gq, const float* gk, int b, int h, int qb, int tid, int wid, int lane, ...
;     ...
;                         const int st = 2 * p + u, sg = 8 * kt + st;
;                         if (sg > tg) {
; #pragma unroll
;                             for (int j = 0; j < 4; ++j) av[u][j] = 0.f;
;                         } else {
;                             const bf16x8 a0 = *(const LAS bf16x8*)(Ks + (16 * st + tq) * 72 + 8 * quad), a1 = *(const LAS bf16x8*)(Ks + (16 * st + tq) * 72 + 32 + 8 * quad);
;                             f32x4 z = (f32x4){0.f, 0.f, 0.f, 0.f};
;                             z = mfma16(a0, Bq0, z); z = mfma16(a1, Bq1, z);
;                             float r[4], be[4];
; #pragma unroll
;                             for (int j = 0; j < 4; ++j) { const float e = fexp2(fminf(z[j], 80.f)); const float rr = frcp(1.0f + e); r[j] = rr; be[j] = e * rr; }
;                             if (sg == tg) {
;                                 int tql = tq; asm volatile("" : "+v"(tql));
; #pragma unroll
;                                 for (int j = 0; j < 4; ++j) if (4 * quad + j >= tql) { r[j] = 1.0f; be[j] = 0.f; }
.LBB0_440:
	ds_read_b128 v[60:63], v138
	ds_read_b128 v[64:67], v138 offset:64
	s_cmp_lg_u32 s41, s78
	s_waitcnt lgkmcnt(1)
	v_mfma_f32_16x16x32_bf16 v[60:63], v[60:63], v[24:27], 0
	s_waitcnt lgkmcnt(0)
	v_mfma_f32_16x16x32_bf16 v[60:63], v[64:67], v[28:31], v[60:63]
	s_nop 7
	v_min_f32_e32 v60, 0x42a00000, v60
	v_min_f32_e32 v61, 0x42a00000, v61
	v_min_f32_e32 v64, 0x42a00000, v62
	v_min_f32_e32 v65, 0x42a00000, v63
	v_exp_f32_e32 v62, v60
	v_exp_f32_e32 v63, v61
	v_exp_f32_e32 v84, v64
	v_exp_f32_e32 v85, v65
	v_pk_add_f32 v[60:61], v[62:63], v[250:251]
	v_pk_add_f32 v[64:65], v[84:85], v[250:251]
	v_rcp_f32_e32 v66, v60
	v_rcp_f32_e32 v67, v61
	v_rcp_f32_e32 v60, v64
	v_rcp_f32_e32 v61, v65
	v_pk_mul_f32 v[64:65], v[62:63], v[66:67]
	v_pk_mul_f32 v[62:63], v[84:85], v[60:61]
	s_cbranch_scc1 .LBB0_442
	v_mov_b32_e32 v84, v93
	s_nop 0
	v_cmp_lt_i32_e64 s[12:13], v129, v84
	v_cmp_lt_i32_e64 s[14:15], v130, v84
	v_cmp_lt_i32_e64 s[10:11], v128, v84
	s_or_b64 s[12:13], s[14:15], s[12:13]
	v_cmp_lt_i32_e32 vcc, v98, v84
	s_or_b64 s[10:11], s[12:13], s[10:11]
	s_or_b64 vcc, s[10:11], vcc
	v_cndmask_b32_e64 v63, 0, v63, s[14:15]
	v_cndmask_b32_e64 v62, 0, v62, s[12:13]
	v_cndmask_b32_e64 v65, 0, v65, s[10:11]
	v_cndmask_b32_e32 v64, 0, v64, vcc
	v_cndmask_b32_e64 v60, 1.0, v60, s[12:13]
	v_cndmask_b32_e64 v67, 1.0, v67, s[10:11]
	v_cndmask_b32_e32 v66, 1.0, v66, vcc
	v_cndmask_b32_e64 v61, 1.0, v61, s[14:15]

; #define LAS __attribute__((address_space(3)))
; __device__ __forceinline__ float fexp2(float x) { return __builtin_amdgcn_exp2f(x); }
; __device__ __forceinline__ float frcp(float x) { return __builtin_amdgcn_rcpf(x); }
; __device__ __forceinline__ f32x4 mfma16(bf16x8 a, bf16x8 b, f32x4 c) { return __builtin_amdgcn_mfma_f32_16x16x32_bf16(a, b, c, 0, 0, 0); }
; __device__ __forceinline__ void attn_unit(LAS unsigned char* lds, const bf16* P, bf16* Y, const float* gq, const float* gk, int b, int h, int qb, int tid, int wid, int lane, ...
;     ...
;                         const int st = 2 * p + u, sg = 8 * kt + st;
;                         if (sg > tg) {
; #pragma unroll
;                             for (int j = 0; j < 4; ++j) av[u][j] = 0.f;
;                         } else {
;                             const bf16x8 a0 = *(const LAS bf16x8*)(Ks + (16 * st + tq) * 72 + 8 * quad), a1 = *(const LAS bf16x8*)(Ks + (16 * st + tq) * 72 + 32 + 8 * quad);
;                             f32x4 z = (f32x4){0.f, 0.f, 0.f, 0.f};
;                             z = mfma16(a0, Bq0, z); z = mfma16(a1, Bq1, z);
;                             float r[4], be[4];
; #pragma unroll
;                             for (int j = 0; j < 4; ++j) { const float e = fexp2(fminf(z[j], 80.f)); const float rr = frcp(1.0f + e); r[j] = rr; be[j] = e * rr; }
;                             if (sg == tg) {
;                                 int tql = tq; asm volatile("" : "+v"(tql));
; #pragma unroll
;                                 for (int j = 0; j < 4; ++j) if (4 * quad + j >= tql) { r[j] = 1.0f; be[j] = 0.f; }
.LBB0_449:
	s_addk_i32 s82, 0x70
	s_cmp_gt_u32 s82, s36
	s_cselect_b64 s[12:13], -1, 0
	s_or_b64 s[12:13], s[12:13], s[10:11]
	s_and_b64 vcc, exec, s[12:13]
	s_cbranch_vccnz .LBB0_470
	s_cmp_ge_u32 s82, s36
	v_mov_b32_e32 v59, 0
	s_cbranch_scc1 .LBB0_460
	ds_read_b128 v[56:59], v136 offset:2304
	ds_read_b128 v[60:63], v136 offset:2368
	s_cmp_lg_u32 s3, s78
	s_waitcnt lgkmcnt(1)
	v_mfma_f32_16x16x32_bf16 v[56:59], v[56:59], v[24:27], 0
	s_waitcnt lgkmcnt(0)
	v_mfma_f32_16x16x32_bf16 v[56:59], v[60:63], v[28:31], v[56:59]
	s_nop 7
	v_min_f32_e32 v56, 0x42a00000, v56
	v_min_f32_e32 v57, 0x42a00000, v57
	v_min_f32_e32 v60, 0x42a00000, v58
	v_min_f32_e32 v61, 0x42a00000, v59
	v_exp_f32_e32 v58, v56
	v_exp_f32_e32 v59, v57
	v_exp_f32_e32 v60, v60
	v_exp_f32_e32 v61, v61
	v_pk_add_f32 v[56:57], v[58:59], v[250:251]
	v_pk_add_f32 v[64:65], v[60:61], v[250:251]
	v_rcp_f32_e32 v62, v56
	v_rcp_f32_e32 v63, v57
	v_rcp_f32_e32 v56, v64
	v_rcp_f32_e32 v57, v65
	v_pk_mul_f32 v[58:59], v[58:59], v[62:63]
	v_pk_mul_f32 v[60:61], v[60:61], v[56:57]
	s_cbranch_scc1 .LBB0_453
	v_mov_b32_e32 v64, v93
	s_nop 0
	v_cmp_lt_i32_e64 s[12:13], v129, v64
	v_cmp_lt_i32_e64 s[14:15], v130, v64
	v_cmp_lt_i32_e64 s[10:11], v128, v64
	s_or_b64 s[12:13], s[14:15], s[12:13]
	v_cmp_lt_i32_e32 vcc, v98, v64
	s_or_b64 s[10:11], s[12:13], s[10:11]
	s_or_b64 vcc, s[10:11], vcc
	v_cndmask_b32_e64 v61, 0, v61, s[14:15]
	v_cndmask_b32_e64 v60, 0, v60, s[12:13]
	v_cndmask_b32_e64 v59, 0, v59, s[10:11]
	v_cndmask_b32_e32 v58, 0, v58, vcc
	v_cndmask_b32_e64 v56, 1.0, v56, s[12:13]
	v_cndmask_b32_e64 v63, 1.0, v63, s[10:11]
	v_cndmask_b32_e32 v62, 1.0, v62, vcc
	v_cndmask_b32_e64 v57, 1.0, v57, s[14:15]

; #define LAS __attribute__((address_space(3)))
; __device__ __forceinline__ float fexp2(float x) { return __builtin_amdgcn_exp2f(x); }
; __device__ __forceinline__ float frcp(float x) { return __builtin_amdgcn_rcpf(x); }
; __device__ __forceinline__ f32x4 mfma16(bf16x8 a, bf16x8 b, f32x4 c) { return __builtin_amdgcn_mfma_f32_16x16x32_bf16(a, b, c, 0, 0, 0); }
; __device__ __forceinline__ void attn_unit(LAS unsigned char* lds, const bf16* P, bf16* Y, const float* gq, const float* gk, int b, int h, int qb, int tid, int wid, int lane, ...
;     ...
;                         const int st = 2 * p + u, sg = 8 * kt + st;
;                         if (sg > tg) {
; #pragma unroll
;                             for (int j = 0; j < 4; ++j) av[u][j] = 0.f;
;                         } else {
;                             const bf16x8 a0 = *(const LAS bf16x8*)(Ks + (16 * st + tq) * 72 + 8 * quad), a1 = *(const LAS bf16x8*)(Ks + (16 * st + tq) * 72 + 32 + 8 * quad);
;                             f32x4 z = (f32x4){0.f, 0.f, 0.f, 0.f};
;                             z = mfma16(a0, Bq0, z); z = mfma16(a1, Bq1, z);
;                             float r[4], be[4];
; #pragma unroll
;                             for (int j = 0; j < 4; ++j) { const float e = fexp2(fminf(z[j], 80.f)); const float rr = frcp(1.0f + e); r[j] = rr; be[j] = e * rr; }
;                             if (sg == tg) {
;                                 int tql = tq; asm volatile("" : "+v"(tql));
; #pragma unroll
;                                 for (int j = 0; j < 4; ++j) if (4 * quad + j >= tql) { r[j] = 1.0f; be[j] = 0.f; }
.LBB0_461:
	ds_read_b128 v[60:63], v136
	ds_read_b128 v[64:67], v136 offset:64
	s_cmp_lg_u32 s33, s78
	s_waitcnt lgkmcnt(1)
	v_mfma_f32_16x16x32_bf16 v[60:63], v[60:63], v[24:27], 0
	s_waitcnt lgkmcnt(0)
	v_mfma_f32_16x16x32_bf16 v[60:63], v[64:67], v[28:31], v[60:63]
	s_nop 7
	v_min_f32_e32 v60, 0x42a00000, v60
	v_min_f32_e32 v61, 0x42a00000, v61
	v_min_f32_e32 v64, 0x42a00000, v62
	v_min_f32_e32 v65, 0x42a00000, v63
	v_exp_f32_e32 v62, v60
	v_exp_f32_e32 v63, v61
	v_exp_f32_e32 v84, v64
	v_exp_f32_e32 v85, v65
	v_pk_add_f32 v[60:61], v[62:63], v[250:251]
	v_pk_add_f32 v[64:65], v[84:85], v[250:251]
	v_rcp_f32_e32 v66, v60
	v_rcp_f32_e32 v67, v61
	v_rcp_f32_e32 v60, v64
	v_rcp_f32_e32 v61, v65
	v_pk_mul_f32 v[64:65], v[62:63], v[66:67]
	v_pk_mul_f32 v[62:63], v[84:85], v[60:61]
	s_cbranch_scc1 .LBB0_463
	v_mov_b32_e32 v84, v93
	s_nop 0
	v_cmp_lt_i32_e64 s[12:13], v129, v84
	v_cmp_lt_i32_e64 s[14:15], v130, v84
	v_cmp_lt_i32_e64 s[10:11], v128, v84
	s_or_b64 s[12:13], s[14:15], s[12:13]
	v_cmp_lt_i32_e32 vcc, v98, v84
	s_or_b64 s[10:11], s[12:13], s[10:11]
	s_or_b64 vcc, s[10:11], vcc
	v_cndmask_b32_e64 v63, 0, v63, s[14:15]
	v_cndmask_b32_e64 v62, 0, v62, s[12:13]
	v_cndmask_b32_e64 v65, 0, v65, s[10:11]
	v_cndmask_b32_e32 v64, 0, v64, vcc
	v_cndmask_b32_e64 v60, 1.0, v60, s[12:13]
	v_cndmask_b32_e64 v67, 1.0, v67, s[10:11]
	v_cndmask_b32_e32 v66, 1.0, v66, vcc
	v_cndmask_b32_e64 v61, 1.0, v61, s[14:15]

; #define LAS __attribute__((address_space(3)))
; __device__ __forceinline__ void attn_unit(LAS unsigned char* lds, const bf16* P, bf16* Y, const float* gq, const float* gk, int b, int h, int qb, int tid, int wid, int lane, ...
;     ...
;                 float kf[8];
; #pragma unroll
;                 for (int i = 0; i < 4; ++i) { kf[2 * i] = blo(kw[hf][i]); kf[2 * i + 1] = bhi(kw[hf][i]); }
;                 float ss = 0.f;
; #pragma unroll
;                 for (int i = 0; i < 8; ++i) ss += kf[i] * kf[i];
;                 ss += __shfl_xor(ss, 1); ss += __shfl_xor(ss, 2); ss += __shfl_xor(ss, 4);
;                 const float rs = __builtin_amdgcn_rsqf(ss * (1.0f / 64.0f) + EPSN);
; #pragma unroll
;                 for (int i = 0; i < 4; ++i) { kf[i] *= rs * gk0[i]; kf[4 + i] *= rs * gk1[i]; }
;                 v4u o; o.x = pk2(kf[0], kf[1]); o.y = pk2(kf[2], kf[3]); o.z = pk2(kf[4], kf[5]); o.w = pk2(kf[6], kf[7]);
;                 *(LAS v4u*)(Ks + (sr + 64 * hf) * 72 + 8 * dc) = o;
; #pragma unroll
;                 for (int i = 0; i < 4; ++i) { Vt[(8 * (dcv + 4 * hf) + 2 * i) * 136 + srv] = (bf16)(vw[hf][i] & 0xffffu); Vt[(8 * (dcv + 4 * hf) + 2 * i + 1) * 136 + srv] = (bf16)(vw[hf][i] >> 16); }
;             }
;         }
;         if (tid == 0) flags[(it + 1) % 3] = 0;
;         LBAR();
;         if (!wdone) {
; #pragma unroll
;             for (int p = 3; p >= 0; --p) {
;                 if (8 * kt + 2 * p <= tg && !wdone) {
;                     float av[2][4];
; #pragma unroll
;                     for (int u = 1; u >= 0; --u) {
;                         const int st = 2 * p + u, sg = 8 * kt + st;
;                         if (sg > tg) {
; #pragma unroll
;                             for (int j = 0; j < 4; ++j) av[u][j] = 0.f;
;                         } else {
;                             const bf16x8 a0 = *(const LAS bf16x8*)(Ks + (16 * st + tq) * 72 + 8 * quad), a1 = *(const LAS bf16x8*)(Ks + (16 * st + tq) * 72 + 32 + 8 * quad);
;                             f32x4 z = (f32x4){0.f, 0.f, 0.f, 0.f};
;                             z = mfma16(a0, Bq0, z); z = mfma16(a1, Bq1, z);
;                             float r[4], be[4];
; #pragma unroll
;                             for (int j = 0; j < 4; ++j) { const float e = fexp2(fminf(z[j], 80.f)); const float rr = frcp(1.0f + e); r[j] = rr; be[j] = e * rr; }
;                             if (sg == tg) {
.LBB0_853:
	v_and_b32_e32 v70, 0xffff0000, v52
	v_lshlrev_b32_e32 v69, 16, v52
	v_mul_f32_e32 v75, v70, v70
	v_lshlrev_b32_e32 v71, 16, v53
	v_fmac_f32_e32 v75, v69, v69
	v_and_b32_e32 v72, 0xffff0000, v53
	v_fmac_f32_e32 v75, v71, v71
	v_lshlrev_b32_e32 v73, 16, v54
	v_fmac_f32_e32 v75, v72, v72
	v_and_b32_e32 v74, 0xffff0000, v54
	v_fmac_f32_e32 v75, v73, v73
	v_and_b32_e32 v52, 0xffff0000, v55
	v_lshlrev_b32_e32 v53, 16, v55
	v_fmac_f32_e32 v75, v74, v74
	v_pk_mul_f32 v[54:55], v[52:53], v[52:53]
	v_lshlrev_b32_e32 v80, 16, v50
	v_add_f32_e32 v55, v55, v75
	v_add_f32_e32 v54, v54, v55
	ds_bpermute_b32 v55, v126, v54
	v_and_b32_e32 v81, 0xffff0000, v50
	v_and_b32_e32 v79, 0xffff0000, v49
	s_waitcnt lgkmcnt(0)
	v_add_f32_e32 v54, v54, v55
	ds_bpermute_b32 v55, v127, v54
	s_waitcnt lgkmcnt(0)
	v_add_f32_e32 v54, v54, v55
	ds_bpermute_b32 v55, v128, v54
	s_waitcnt lgkmcnt(0)
	v_add_f32_e32 v54, v54, v55
	v_fmamk_f32 v54, v54, 0x3c800000, v142
	v_rsq_f32_e32 v75, v54
	s_waitcnt vmcnt(1)
	v_mul_f32_e32 v77, v33, v75
	s_waitcnt vmcnt(0)
	v_mul_f32_e32 v76, v37, v75
	v_mul_f32_e32 v74, v77, v74
	v_and_b32_e32 v77, 0xffff0000, v48
	v_mul_f32_e32 v78, v38, v75
	v_mul_f32_e32 v70, v76, v70
	v_lshlrev_b32_e32 v76, 16, v48
	v_mul_f32_e32 v50, v77, v77
	v_mul_f32_e32 v54, v36, v75
	v_mul_f32_e32 v71, v78, v71
	v_lshlrev_b32_e32 v78, 16, v49
	v_fmac_f32_e32 v50, v76, v76
	v_mul_f32_e32 v69, v54, v69
	v_mul_f32_e32 v54, v34, v75
	v_fmac_f32_e32 v50, v78, v78
	v_mul_f32_e32 v55, v32, v75
	v_mul_f32_e32 v53, v54, v53
	v_mul_f32_e32 v54, v39, v75
	v_fmac_f32_e32 v50, v79, v79
	v_mul_f32_e32 v73, v55, v73
	v_mul_f32_e32 v72, v54, v72
	v_fmac_f32_e32 v50, v80, v80
	v_and_b32_e32 v54, 0xffff0000, v51
	v_lshlrev_b32_e32 v55, 16, v51
	v_fmac_f32_e32 v50, v81, v81
	v_pk_mul_f32 v[48:49], v[54:55], v[54:55]
	s_nop 0
	v_add_f32_e32 v49, v49, v50
	v_add_f32_e32 v50, v48, v49
	ds_bpermute_b32 v51, v126, v50
	v_mul_f32_e32 v48, v35, v75
	v_mul_f32_e32 v52, v48, v52
	v_cvt_pk_bf16_f32 v48, v69, v70
	v_cvt_pk_bf16_f32 v49, v71, v72
	s_waitcnt lgkmcnt(0)
	v_add_f32_e32 v69, v50, v51
	ds_bpermute_b32 v70, v127, v69
	v_cvt_pk_bf16_f32 v50, v73, v74
	v_cvt_pk_bf16_f32 v51, v53, v52
	ds_write_b128 v145, v[48:51]
	ds_write_b16 v129, v44 offset:18432
	ds_write_b16_d16_hi v129, v44 offset:18704
	ds_write_b16 v129, v45 offset:18976
	ds_write_b16_d16_hi v129, v45 offset:19248
	ds_write_b16 v129, v46 offset:19520
	s_waitcnt lgkmcnt(6)
	v_add_f32_e32 v48, v69, v70
	ds_bpermute_b32 v49, v128, v48
	ds_write_b16_d16_hi v129, v46 offset:19792
	ds_write_b16 v129, v47 offset:20064
	ds_write_b16_d16_hi v129, v47 offset:20336
	s_waitcnt lgkmcnt(3)
	v_add_f32_e32 v44, v48, v49
	v_fmamk_f32 v44, v44, 0x3c800000, v142
	v_rsq_f32_e32 v44, v44
	s_nop 0
	v_mul_f32_e32 v45, v36, v44
	v_mul_f32_e32 v46, v32, v44
	v_mul_f32_e32 v47, v37, v44
	v_mul_f32_e32 v45, v45, v76
	v_mul_f32_e32 v46, v46, v80
	v_mul_f32_e32 v47, v47, v77
	v_mul_f32_e32 v48, v33, v44
	v_mul_f32_e32 v49, v38, v44
	v_mul_f32_e32 v50, v34, v44
	v_mul_f32_e32 v51, v39, v44
	v_mul_f32_e32 v44, v35, v44
	v_mul_f32_e32 v48, v48, v81
	v_mul_f32_e32 v49, v49, v78
	v_mul_f32_e32 v50, v50, v55
	v_mul_f32_e32 v51, v51, v79
	v_mul_f32_e32 v52, v44, v54
	v_cvt_pk_bf16_f32 v44, v45, v47
	v_cvt_pk_bf16_f32 v45, v49, v51
	v_cvt_pk_bf16_f32 v46, v46, v48
	v_cvt_pk_bf16_f32 v47, v50, v52
	ds_write_b128 v145, v[44:47] offset:9216
	ds_write_b16 v129, v40 offset:27136
	ds_write_b16_d16_hi v129, v40 offset:27408
	ds_write_b16 v129, v41 offset:27680
	ds_write_b16_d16_hi v129, v41 offset:27952
	ds_write_b16 v129, v42 offset:28224
	ds_write_b16_d16_hi v129, v42 offset:28496
	ds_write_b16 v129, v43 offset:28768
	ds_write_b16_d16_hi v129, v43 offset:29040
	s_mov_b64 s[10:11], exec
	v_readlane_b32 s12, v249, 8
	v_readlane_b32 s13, v249, 9
	s_and_b64 s[12:13], s[10:11], s[12:13]
	s_mov_b64 exec, s[12:13]
	ds_write_b32 v95, v95 offset:35844
	s_or_b64 exec, exec, s[10:11]
	s_waitcnt lgkmcnt(0)
	s_barrier
	s_andn2_b64 vcc, exec, s[0:1]
	s_cbranch_vccnz .LBB0_866
	s_andn2_b64 vcc, exec, s[18:19]
	s_cbranch_vccnz .LBB0_867
	ds_read_b128 v[40:43], v137
	ds_read_b128 v[44:47], v137 offset:64
	s_andn2_b64 vcc, exec, s[20:21]
	s_waitcnt lgkmcnt(1)
	v_mfma_f32_16x16x32_bf16 v[40:43], v[40:43], v[24:27], 0
	s_waitcnt lgkmcnt(0)
	v_mfma_f32_16x16x32_bf16 v[40:43], v[44:47], v[28:31], v[40:43]
	s_nop 7
	v_min_f32_e32 v40, 0x42a00000, v40
	v_min_f32_e32 v41, 0x42a00000, v41
	v_min_f32_e32 v42, 0x42a00000, v42
	v_min_f32_e32 v43, 0x42a00000, v43
	v_exp_f32_e32 v40, v40
	v_exp_f32_e32 v41, v41
	v_exp_f32_e32 v46, v42
	v_exp_f32_e32 v47, v43
	v_pk_add_f32 v[42:43], v[40:41], v[250:251]
	v_pk_add_f32 v[44:45], v[46:47], v[250:251]
	v_rcp_f32_e32 v48, v42
	v_rcp_f32_e32 v49, v43
	v_rcp_f32_e32 v44, v44
	v_rcp_f32_e32 v45, v45
	v_pk_mul_f32 v[42:43], v[40:41], v[48:49]
	v_pk_mul_f32 v[40:41], v[46:47], v[44:45]
	s_cbranch_vccnz .LBB0_859
	v_mov_b32_e32 v46, v91
	s_nop 0
	v_cmp_lt_i32_e64 s[12:13], v131, v46
	v_cmp_lt_i32_e64 s[14:15], v132, v46
	v_cmp_lt_i32_e64 s[10:11], v130, v46
	s_or_b64 s[12:13], s[14:15], s[12:13]
	v_cmp_lt_i32_e32 vcc, v98, v46
	s_or_b64 s[10:11], s[12:13], s[10:11]
	s_or_b64 vcc, s[10:11], vcc
	v_cndmask_b32_e64 v41, 0, v41, s[14:15]
	v_cndmask_b32_e64 v40, 0, v40, s[12:13]
	v_cndmask_b32_e64 v43, 0, v43, s[10:11]
	v_cndmask_b32_e32 v42, 0, v42, vcc
	v_cndmask_b32_e64 v44, 1.0, v44, s[12:13]
	v_cndmask_b32_e64 v49, 1.0, v49, s[10:11]
	v_cndmask_b32_e32 v48, 1.0, v48, vcc
	v_cndmask_b32_e64 v45, 1.0, v45, s[14:15]

; #define LAS __attribute__((address_space(3)))
; __device__ __forceinline__ float fexp2(float x) { return __builtin_amdgcn_exp2f(x); }
; __device__ __forceinline__ float frcp(float x) { return __builtin_amdgcn_rcpf(x); }
; __device__ __forceinline__ f32x4 mfma16(bf16x8 a, bf16x8 b, f32x4 c) { return __builtin_amdgcn_mfma_f32_16x16x32_bf16(a, b, c, 0, 0, 0); }
; __device__ __forceinline__ void attn_unit(LAS unsigned char* lds, const bf16* P, bf16* Y, const float* gq, const float* gk, int b, int h, int qb, int tid, int wid, int lane, ...
;     ...
;                             const bf16x8 a0 = *(const LAS bf16x8*)(Ks + (16 * st + tq) * 72 + 8 * quad), a1 = *(const LAS bf16x8*)(Ks + (16 * st + tq) * 72 + 32 + 8 * quad);
;                             f32x4 z = (f32x4){0.f, 0.f, 0.f, 0.f};
;                             z = mfma16(a0, Bq0, z); z = mfma16(a1, Bq1, z);
;                             float r[4], be[4];
; #pragma unroll
;                             for (int j = 0; j < 4; ++j) { const float e = fexp2(fminf(z[j], 80.f)); const float rr = frcp(1.0f + e); r[j] = rr; be[j] = e * rr; }
;                             if (sg == tg) {
;                                 int tql = tq; asm volatile("" : "+v"(tql));
; #pragma unroll
;                                 for (int j = 0; j < 4; ++j) if (4 * quad + j >= tql) { r[j] = 1.0f; be[j] = 0.f; }
.LBB0_868:
	ds_read_b128 v[44:47], v138 offset:13824
	ds_read_b128 v[48:51], v138 offset:13888
	s_andn2_b64 vcc, exec, s[16:17]
	s_waitcnt lgkmcnt(1)
	v_mfma_f32_16x16x32_bf16 v[44:47], v[44:47], v[24:27], 0
	s_waitcnt lgkmcnt(0)
	v_mfma_f32_16x16x32_bf16 v[44:47], v[48:51], v[28:31], v[44:47]
	s_nop 7
	v_min_f32_e32 v44, 0x42a00000, v44
	v_min_f32_e32 v45, 0x42a00000, v45
	v_min_f32_e32 v48, 0x42a00000, v46
	v_min_f32_e32 v49, 0x42a00000, v47
	v_exp_f32_e32 v46, v44
	v_exp_f32_e32 v47, v45
	v_exp_f32_e32 v52, v48
	v_exp_f32_e32 v53, v49
	v_pk_add_f32 v[44:45], v[46:47], v[250:251]
	v_pk_add_f32 v[48:49], v[52:53], v[250:251]
	v_rcp_f32_e32 v50, v44
	v_rcp_f32_e32 v51, v45
	v_rcp_f32_e32 v44, v48
	v_rcp_f32_e32 v45, v49
	v_pk_mul_f32 v[48:49], v[46:47], v[50:51]
	v_pk_mul_f32 v[46:47], v[52:53], v[44:45]
	s_cbranch_vccnz .LBB0_870
	v_mov_b32_e32 v52, v91
	s_nop 0
	v_cmp_lt_i32_e64 s[12:13], v131, v52
	v_cmp_lt_i32_e64 s[14:15], v132, v52
	v_cmp_lt_i32_e64 s[10:11], v130, v52
	s_or_b64 s[12:13], s[14:15], s[12:13]
	v_cmp_lt_i32_e32 vcc, v98, v52
	s_or_b64 s[10:11], s[12:13], s[10:11]
	s_or_b64 vcc, s[10:11], vcc
	v_cndmask_b32_e64 v47, 0, v47, s[14:15]
	v_cndmask_b32_e64 v46, 0, v46, s[12:13]
	v_cndmask_b32_e64 v49, 0, v49, s[10:11]
	v_cndmask_b32_e32 v48, 0, v48, vcc
	v_cndmask_b32_e64 v44, 1.0, v44, s[12:13]
	v_cndmask_b32_e64 v51, 1.0, v51, s[10:11]
	v_cndmask_b32_e32 v50, 1.0, v50, vcc
	v_cndmask_b32_e64 v45, 1.0, v45, s[14:15]

; #define LAS __attribute__((address_space(3)))
; __device__ __forceinline__ float fexp2(float x) { return __builtin_amdgcn_exp2f(x); }
; __device__ __forceinline__ float frcp(float x) { return __builtin_amdgcn_rcpf(x); }
; __device__ __forceinline__ f32x4 mfma16(bf16x8 a, bf16x8 b, f32x4 c) { return __builtin_amdgcn_mfma_f32_16x16x32_bf16(a, b, c, 0, 0, 0); }
; #define LBAR() do { asm volatile("s_waitcnt lgkmcnt(0)" ::: "memory"); __builtin_amdgcn_s_barrier(); asm volatile("" ::: "memory"); } while (0)
; __device__ __forceinline__ void attn_unit(LAS unsigned char* lds, const bf16* P, bf16* Y, const float* gq, const float* gk, int b, int h, int qb, int tid, int wid, int lane, ...
;     ...
;         if (tid == 0) flags[(it + 1) % 3] = 0;
;         LBAR();
;         if (!wdone) {
; #pragma unroll
;             for (int p = 3; p >= 0; --p) {
;                 if (8 * kt + 2 * p <= tg && !wdone) {
;                     float av[2][4];
; #pragma unroll
;                     for (int u = 1; u >= 0; --u) {
;                         const int st = 2 * p + u, sg = 8 * kt + st;
;                         if (sg > tg) {
; #pragma unroll
;                             for (int j = 0; j < 4; ++j) av[u][j] = 0.f;
;                         } else {
;                             const bf16x8 a0 = *(const LAS bf16x8*)(Ks + (16 * st + tq) * 72 + 8 * quad), a1 = *(const LAS bf16x8*)(Ks + (16 * st + tq) * 72 + 32 + 8 * quad);
;                             f32x4 z = (f32x4){0.f, 0.f, 0.f, 0.f};
;                             z = mfma16(a0, Bq0, z); z = mfma16(a1, Bq1, z);
;                             float r[4], be[4];
; #pragma unroll
;                             for (int j = 0; j < 4; ++j) { const float e = fexp2(fminf(z[j], 80.f)); const float rr = frcp(1.0f + e); r[j] = rr; be[j] = e * rr; }
;                             if (sg == tg) {
;                                 int tql = tq; asm volatile("" : "+v"(tql));
; #pragma unroll
;                                 for (int j = 0; j < 4; ++j) if (4 * quad + j >= tql) { r[j] = 1.0f; be[j] = 0.f; }
.LBB0_909:
	s_or_b64 exec, exec, s[12:13]
	s_xor_b64 s[12:13], s[10:11], -1
	s_mul_hi_u32 s10, s73, 0xaaaaaaab
	s_waitcnt lgkmcnt(0)
	s_barrier
	s_lshr_b32 s79, s10, 1
	s_mul_i32 s79, s79, -12
	s_mov_b64 s[10:11], -1
	s_and_saveexec_b64 s[64:65], s[12:13]
	s_cbranch_execz .LBB0_997
	s_add_i32 s80, s72, s76
	s_add_i32 s10, s80, 0x76
	s_cmp_gt_u32 s10, s41
	s_mov_b64 s[10:11], 0
	s_cbranch_scc1 .LBB0_931
	s_add_i32 s10, s80, 0x77
	s_cmp_gt_u32 s10, s41
	v_mov_b32_e32 v59, 0
	s_cbranch_scc1 .LBB0_921
	ds_read_b128 v[56:59], v137
	ds_read_b128 v[60:63], v137 offset:64
	s_cmp_lg_u32 s52, s76
	s_waitcnt lgkmcnt(1)
	v_mfma_f32_16x16x32_bf16 v[56:59], v[56:59], v[24:27], 0
	s_waitcnt lgkmcnt(0)
	v_mfma_f32_16x16x32_bf16 v[56:59], v[60:63], v[28:31], v[56:59]
	s_nop 7
	v_min_f32_e32 v56, 0x42a00000, v56
	v_min_f32_e32 v57, 0x42a00000, v57
	v_min_f32_e32 v60, 0x42a00000, v58
	v_min_f32_e32 v61, 0x42a00000, v59
	v_exp_f32_e32 v58, v56
	v_exp_f32_e32 v59, v57
	v_exp_f32_e32 v60, v60
	v_exp_f32_e32 v61, v61
	v_pk_add_f32 v[56:57], v[58:59], v[250:251]
	v_pk_add_f32 v[64:65], v[60:61], v[250:251]
	v_rcp_f32_e32 v62, v56
	v_rcp_f32_e32 v63, v57
	v_rcp_f32_e32 v56, v64
	v_rcp_f32_e32 v57, v65
	v_pk_mul_f32 v[58:59], v[58:59], v[62:63]
	v_pk_mul_f32 v[60:61], v[60:61], v[56:57]
	s_cbranch_scc1 .LBB0_914
	v_mov_b32_e32 v64, v91
	s_nop 0
	v_cmp_lt_i32_e64 s[12:13], v131, v64
	v_cmp_lt_i32_e64 s[14:15], v132, v64
	v_cmp_lt_i32_e64 s[10:11], v130, v64
	s_or_b64 s[12:13], s[14:15], s[12:13]
	v_cmp_lt_i32_e32 vcc, v98, v64
	s_or_b64 s[10:11], s[12:13], s[10:11]
	s_or_b64 vcc, s[10:11], vcc
	v_cndmask_b32_e64 v61, 0, v61, s[14:15]
	v_cndmask_b32_e64 v60, 0, v60, s[12:13]
	v_cndmask_b32_e64 v59, 0, v59, s[10:11]
	v_cndmask_b32_e32 v58, 0, v58, vcc
	v_cndmask_b32_e64 v56, 1.0, v56, s[12:13]
	v_cndmask_b32_e64 v63, 1.0, v63, s[10:11]
	v_cndmask_b32_e32 v62, 1.0, v62, vcc
	v_cndmask_b32_e64 v57, 1.0, v57, s[14:15]

; #define LAS __attribute__((address_space(3)))
; __device__ __forceinline__ float fexp2(float x) { return __builtin_amdgcn_exp2f(x); }
; __device__ __forceinline__ float frcp(float x) { return __builtin_amdgcn_rcpf(x); }
; __device__ __forceinline__ f32x4 mfma16(bf16x8 a, bf16x8 b, f32x4 c) { return __builtin_amdgcn_mfma_f32_16x16x32_bf16(a, b, c, 0, 0, 0); }
; __device__ __forceinline__ void attn_unit(LAS unsigned char* lds, const bf16* P, bf16* Y, const float* gq, const float* gk, int b, int h, int qb, int tid, int wid, int lane, ...
;     ...
;                         const int st = 2 * p + u, sg = 8 * kt + st;
;                         if (sg > tg) {
; #pragma unroll
;                             for (int j = 0; j < 4; ++j) av[u][j] = 0.f;
;                         } else {
;                             const bf16x8 a0 = *(const LAS bf16x8*)(Ks + (16 * st + tq) * 72 + 8 * quad), a1 = *(const LAS bf16x8*)(Ks + (16 * st + tq) * 72 + 32 + 8 * quad);
;                             f32x4 z = (f32x4){0.f, 0.f, 0.f, 0.f};
;                             z = mfma16(a0, Bq0, z); z = mfma16(a1, Bq1, z);
;                             float r[4], be[4];
; #pragma unroll
;                             for (int j = 0; j < 4; ++j) { const float e = fexp2(fminf(z[j], 80.f)); const float rr = frcp(1.0f + e); r[j] = rr; be[j] = e * rr; }
;                             if (sg == tg) {
;                                 int tql = tq; asm volatile("" : "+v"(tql));
; #pragma unroll
;                                 for (int j = 0; j < 4; ++j) if (4 * quad + j >= tql) { r[j] = 1.0f; be[j] = 0.f; }
.LBB0_922:
	ds_read_b128 v[60:63], v138 offset:13824
	ds_read_b128 v[64:67], v138 offset:13888
	s_cmp_lg_u32 s53, s76
	s_waitcnt lgkmcnt(1)
	v_mfma_f32_16x16x32_bf16 v[60:63], v[60:63], v[24:27], 0
	s_waitcnt lgkmcnt(0)
	v_mfma_f32_16x16x32_bf16 v[60:63], v[64:67], v[28:31], v[60:63]
	s_nop 7
	v_min_f32_e32 v60, 0x42a00000, v60
	v_min_f32_e32 v61, 0x42a00000, v61
	v_min_f32_e32 v64, 0x42a00000, v62
	v_min_f32_e32 v65, 0x42a00000, v63
	v_exp_f32_e32 v62, v60
	v_exp_f32_e32 v63, v61
	v_exp_f32_e32 v84, v64
	v_exp_f32_e32 v85, v65
	v_pk_add_f32 v[60:61], v[62:63], v[250:251]
	v_pk_add_f32 v[64:65], v[84:85], v[250:251]
	v_rcp_f32_e32 v66, v60
	v_rcp_f32_e32 v67, v61
	v_rcp_f32_e32 v60, v64
	v_rcp_f32_e32 v61, v65
	v_pk_mul_f32 v[64:65], v[62:63], v[66:67]
	v_pk_mul_f32 v[62:63], v[84:85], v[60:61]
	s_cbranch_scc1 .LBB0_924
	v_mov_b32_e32 v84, v91
	s_nop 0
	v_cmp_lt_i32_e64 s[12:13], v131, v84
	v_cmp_lt_i32_e64 s[14:15], v132, v84
	v_cmp_lt_i32_e64 s[10:11], v130, v84
	s_or_b64 s[12:13], s[14:15], s[12:13]
	v_cmp_lt_i32_e32 vcc, v98, v84
	s_or_b64 s[10:11], s[12:13], s[10:11]
	s_or_b64 vcc, s[10:11], vcc
	v_cndmask_b32_e64 v63, 0, v63, s[14:15]
	v_cndmask_b32_e64 v62, 0, v62, s[12:13]
	v_cndmask_b32_e64 v65, 0, v65, s[10:11]
	v_cndmask_b32_e32 v64, 0, v64, vcc
	v_cndmask_b32_e64 v60, 1.0, v60, s[12:13]
	v_cndmask_b32_e64 v67, 1.0, v67, s[10:11]
	v_cndmask_b32_e32 v66, 1.0, v66, vcc
	v_cndmask_b32_e64 v61, 1.0, v61, s[14:15]

; #define LAS __attribute__((address_space(3)))
; __device__ __forceinline__ float fexp2(float x) { return __builtin_amdgcn_exp2f(x); }
; __device__ __forceinline__ float frcp(float x) { return __builtin_amdgcn_rcpf(x); }
; __device__ __forceinline__ f32x4 mfma16(bf16x8 a, bf16x8 b, f32x4 c) { return __builtin_amdgcn_mfma_f32_16x16x32_bf16(a, b, c, 0, 0, 0); }
; __device__ __forceinline__ void attn_unit(LAS unsigned char* lds, const bf16* P, bf16* Y, const float* gq, const float* gk, int b, int h, int qb, int tid, int wid, int lane, ...
;     ...
;                         const int st = 2 * p + u, sg = 8 * kt + st;
;                         if (sg > tg) {
; #pragma unroll
;                             for (int j = 0; j < 4; ++j) av[u][j] = 0.f;
;                         } else {
;                             const bf16x8 a0 = *(const LAS bf16x8*)(Ks + (16 * st + tq) * 72 + 8 * quad), a1 = *(const LAS bf16x8*)(Ks + (16 * st + tq) * 72 + 32 + 8 * quad);
;                             f32x4 z = (f32x4){0.f, 0.f, 0.f, 0.f};
;                             z = mfma16(a0, Bq0, z); z = mfma16(a1, Bq1, z);
;                             float r[4], be[4];
; #pragma unroll
;                             for (int j = 0; j < 4; ++j) { const float e = fexp2(fminf(z[j], 80.f)); const float rr = frcp(1.0f + e); r[j] = rr; be[j] = e * rr; }
;                             if (sg == tg) {
;                                 int tql = tq; asm volatile("" : "+v"(tql));
; #pragma unroll
;                                 for (int j = 0; j < 4; ++j) if (4 * quad + j >= tql) { r[j] = 1.0f; be[j] = 0.f; }
.LBB0_931:
	s_add_i32 s12, s80, 0x74
	s_cmp_gt_u32 s12, s41
	s_cselect_b64 s[12:13], -1, 0
	s_or_b64 s[12:13], s[12:13], s[10:11]
	s_and_b64 vcc, exec, s[12:13]
	s_cbranch_vccnz .LBB0_952
	s_add_i32 s10, s80, 0x75
	s_cmp_gt_u32 s10, s41
	v_mov_b32_e32 v59, 0
	s_cbranch_scc1 .LBB0_942
	ds_read_b128 v[56:59], v138 offset:11520
	ds_read_b128 v[60:63], v138 offset:11584
	s_cmp_lg_u32 s50, s76
	s_waitcnt lgkmcnt(1)
	v_mfma_f32_16x16x32_bf16 v[56:59], v[56:59], v[24:27], 0
	s_waitcnt lgkmcnt(0)
	v_mfma_f32_16x16x32_bf16 v[56:59], v[60:63], v[28:31], v[56:59]
	s_nop 7
	v_min_f32_e32 v56, 0x42a00000, v56
	v_min_f32_e32 v57, 0x42a00000, v57
	v_min_f32_e32 v60, 0x42a00000, v58
	v_min_f32_e32 v61, 0x42a00000, v59
	v_exp_f32_e32 v58, v56
	v_exp_f32_e32 v59, v57
	v_exp_f32_e32 v60, v60
	v_exp_f32_e32 v61, v61
	v_pk_add_f32 v[56:57], v[58:59], v[250:251]
	v_pk_add_f32 v[64:65], v[60:61], v[250:251]
	v_rcp_f32_e32 v62, v56
	v_rcp_f32_e32 v63, v57
	v_rcp_f32_e32 v56, v64
	v_rcp_f32_e32 v57, v65
	v_pk_mul_f32 v[58:59], v[58:59], v[62:63]
	v_pk_mul_f32 v[60:61], v[60:61], v[56:57]
	s_cbranch_scc1 .LBB0_935
	v_mov_b32_e32 v64, v91
	s_nop 0
	v_cmp_lt_i32_e64 s[12:13], v131, v64
	v_cmp_lt_i32_e64 s[14:15], v132, v64
	v_cmp_lt_i32_e64 s[10:11], v130, v64
	s_or_b64 s[12:13], s[14:15], s[12:13]
	v_cmp_lt_i32_e32 vcc, v98, v64
	s_or_b64 s[10:11], s[12:13], s[10:11]
	s_or_b64 vcc, s[10:11], vcc
	v_cndmask_b32_e64 v61, 0, v61, s[14:15]
	v_cndmask_b32_e64 v60, 0, v60, s[12:13]
	v_cndmask_b32_e64 v59, 0, v59, s[10:11]
	v_cndmask_b32_e32 v58, 0, v58, vcc
	v_cndmask_b32_e64 v56, 1.0, v56, s[12:13]
	v_cndmask_b32_e64 v63, 1.0, v63, s[10:11]
	v_cndmask_b32_e32 v62, 1.0, v62, vcc
	v_cndmask_b32_e64 v57, 1.0, v57, s[14:15]

; #define LAS __attribute__((address_space(3)))
; __device__ __forceinline__ float fexp2(float x) { return __builtin_amdgcn_exp2f(x); }
; __device__ __forceinline__ float frcp(float x) { return __builtin_amdgcn_rcpf(x); }
; __device__ __forceinline__ f32x4 mfma16(bf16x8 a, bf16x8 b, f32x4 c) { return __builtin_amdgcn_mfma_f32_16x16x32_bf16(a, b, c, 0, 0, 0); }
; __device__ __forceinline__ void attn_unit(LAS unsigned char* lds, const bf16* P, bf16* Y, const float* gq, const float* gk, int b, int h, int qb, int tid, int wid, int lane, ...
;     ...
;                         const int st = 2 * p + u, sg = 8 * kt + st;
;                         if (sg > tg) {
; #pragma unroll
;                             for (int j = 0; j < 4; ++j) av[u][j] = 0.f;
;                         } else {
;                             const bf16x8 a0 = *(const LAS bf16x8*)(Ks + (16 * st + tq) * 72 + 8 * quad), a1 = *(const LAS bf16x8*)(Ks + (16 * st + tq) * 72 + 32 + 8 * quad);
;                             f32x4 z = (f32x4){0.f, 0.f, 0.f, 0.f};
;                             z = mfma16(a0, Bq0, z); z = mfma16(a1, Bq1, z);
;                             float r[4], be[4];
; #pragma unroll
;                             for (int j = 0; j < 4; ++j) { const float e = fexp2(fminf(z[j], 80.f)); const float rr = frcp(1.0f + e); r[j] = rr; be[j] = e * rr; }
;                             if (sg == tg) {
;                                 int tql = tq; asm volatile("" : "+v"(tql));
; #pragma unroll
;                                 for (int j = 0; j < 4; ++j) if (4 * quad + j >= tql) { r[j] = 1.0f; be[j] = 0.f; }
.LBB0_943:
	ds_read_b128 v[60:63], v138 offset:9216
	ds_read_b128 v[64:67], v138 offset:9280
	s_cmp_lg_u32 s51, s76
	s_waitcnt lgkmcnt(1)
	v_mfma_f32_16x16x32_bf16 v[60:63], v[60:63], v[24:27], 0
	s_waitcnt lgkmcnt(0)
	v_mfma_f32_16x16x32_bf16 v[60:63], v[64:67], v[28:31], v[60:63]
	s_nop 7
	v_min_f32_e32 v60, 0x42a00000, v60
	v_min_f32_e32 v61, 0x42a00000, v61
	v_min_f32_e32 v64, 0x42a00000, v62
	v_min_f32_e32 v65, 0x42a00000, v63
	v_exp_f32_e32 v62, v60
	v_exp_f32_e32 v63, v61
	v_exp_f32_e32 v84, v64
	v_exp_f32_e32 v85, v65
	v_pk_add_f32 v[60:61], v[62:63], v[250:251]
	v_pk_add_f32 v[64:65], v[84:85], v[250:251]
	v_rcp_f32_e32 v66, v60
	v_rcp_f32_e32 v67, v61
	v_rcp_f32_e32 v60, v64
	v_rcp_f32_e32 v61, v65
	v_pk_mul_f32 v[64:65], v[62:63], v[66:67]
	v_pk_mul_f32 v[62:63], v[84:85], v[60:61]
	s_cbranch_scc1 .LBB0_945
	v_mov_b32_e32 v84, v91
	s_nop 0
	v_cmp_lt_i32_e64 s[12:13], v131, v84
	v_cmp_lt_i32_e64 s[14:15], v132, v84
	v_cmp_lt_i32_e64 s[10:11], v130, v84
	s_or_b64 s[12:13], s[14:15], s[12:13]
	v_cmp_lt_i32_e32 vcc, v98, v84
	s_or_b64 s[10:11], s[12:13], s[10:11]
	s_or_b64 vcc, s[10:11], vcc
	v_cndmask_b32_e64 v63, 0, v63, s[14:15]
	v_cndmask_b32_e64 v62, 0, v62, s[12:13]
	v_cndmask_b32_e64 v65, 0, v65, s[10:11]
	v_cndmask_b32_e32 v64, 0, v64, vcc
	v_cndmask_b32_e64 v60, 1.0, v60, s[12:13]
	v_cndmask_b32_e64 v67, 1.0, v67, s[10:11]
	v_cndmask_b32_e32 v66, 1.0, v66, vcc
	v_cndmask_b32_e64 v61, 1.0, v61, s[14:15]

; #define LAS __attribute__((address_space(3)))
; __device__ __forceinline__ float fexp2(float x) { return __builtin_amdgcn_exp2f(x); }
; __device__ __forceinline__ float frcp(float x) { return __builtin_amdgcn_rcpf(x); }
; __device__ __forceinline__ f32x4 mfma16(bf16x8 a, bf16x8 b, f32x4 c) { return __builtin_amdgcn_mfma_f32_16x16x32_bf16(a, b, c, 0, 0, 0); }
; __device__ __forceinline__ void attn_unit(LAS unsigned char* lds, const bf16* P, bf16* Y, const float* gq, const float* gk, int b, int h, int qb, int tid, int wid, int lane, ...
;     ...
;                         const int st = 2 * p + u, sg = 8 * kt + st;
;                         if (sg > tg) {
; #pragma unroll
;                             for (int j = 0; j < 4; ++j) av[u][j] = 0.f;
;                         } else {
;                             const bf16x8 a0 = *(const LAS bf16x8*)(Ks + (16 * st + tq) * 72 + 8 * quad), a1 = *(const LAS bf16x8*)(Ks + (16 * st + tq) * 72 + 32 + 8 * quad);
;                             f32x4 z = (f32x4){0.f, 0.f, 0.f, 0.f};
;                             z = mfma16(a0, Bq0, z); z = mfma16(a1, Bq1, z);
;                             float r[4], be[4];
; #pragma unroll
;                             for (int j = 0; j < 4; ++j) { const float e = fexp2(fminf(z[j], 80.f)); const float rr = frcp(1.0f + e); r[j] = rr; be[j] = e * rr; }
;                             if (sg == tg) {
;                                 int tql = tq; asm volatile("" : "+v"(tql));
; #pragma unroll
;                                 for (int j = 0; j < 4; ++j) if (4 * quad + j >= tql) { r[j] = 1.0f; be[j] = 0.f; }
.LBB0_952:
	s_add_i32 s12, s80, 0x72
	s_cmp_gt_u32 s12, s41
	s_cselect_b64 s[12:13], -1, 0
	s_or_b64 s[12:13], s[12:13], s[10:11]
	s_and_b64 vcc, exec, s[12:13]
	s_cbranch_vccnz .LBB0_973
	s_add_i32 s10, s80, 0x73
	s_cmp_gt_u32 s10, s41
	v_mov_b32_e32 v59, 0
	s_cbranch_scc1 .LBB0_963
	ds_read_b128 v[56:59], v140
	ds_read_b128 v[60:63], v140 offset:64
	s_cmp_lg_u32 s48, s76
	s_waitcnt lgkmcnt(1)
	v_mfma_f32_16x16x32_bf16 v[56:59], v[56:59], v[24:27], 0
	s_waitcnt lgkmcnt(0)
	v_mfma_f32_16x16x32_bf16 v[56:59], v[60:63], v[28:31], v[56:59]
	s_nop 7
	v_min_f32_e32 v56, 0x42a00000, v56
	v_min_f32_e32 v57, 0x42a00000, v57
	v_min_f32_e32 v60, 0x42a00000, v58
	v_min_f32_e32 v61, 0x42a00000, v59
	v_exp_f32_e32 v58, v56
	v_exp_f32_e32 v59, v57
	v_exp_f32_e32 v60, v60
	v_exp_f32_e32 v61, v61
	v_pk_add_f32 v[56:57], v[58:59], v[250:251]
	v_pk_add_f32 v[64:65], v[60:61], v[250:251]
	v_rcp_f32_e32 v62, v56
	v_rcp_f32_e32 v63, v57
	v_rcp_f32_e32 v56, v64
	v_rcp_f32_e32 v57, v65
	v_pk_mul_f32 v[58:59], v[58:59], v[62:63]
	v_pk_mul_f32 v[60:61], v[60:61], v[56:57]
	s_cbranch_scc1 .LBB0_956
	v_mov_b32_e32 v64, v91
	s_nop 0
	v_cmp_lt_i32_e64 s[12:13], v131, v64
	v_cmp_lt_i32_e64 s[14:15], v132, v64
	v_cmp_lt_i32_e64 s[10:11], v130, v64
	s_or_b64 s[12:13], s[14:15], s[12:13]
	v_cmp_lt_i32_e32 vcc, v98, v64
	s_or_b64 s[10:11], s[12:13], s[10:11]
	s_or_b64 vcc, s[10:11], vcc
	v_cndmask_b32_e64 v61, 0, v61, s[14:15]
	v_cndmask_b32_e64 v60, 0, v60, s[12:13]
	v_cndmask_b32_e64 v59, 0, v59, s[10:11]
	v_cndmask_b32_e32 v58, 0, v58, vcc
	v_cndmask_b32_e64 v56, 1.0, v56, s[12:13]
	v_cndmask_b32_e64 v63, 1.0, v63, s[10:11]
	v_cndmask_b32_e32 v62, 1.0, v62, vcc
	v_cndmask_b32_e64 v57, 1.0, v57, s[14:15]

; #define LAS __attribute__((address_space(3)))
; __device__ __forceinline__ float fexp2(float x) { return __builtin_amdgcn_exp2f(x); }
; __device__ __forceinline__ float frcp(float x) { return __builtin_amdgcn_rcpf(x); }
; __device__ __forceinline__ f32x4 mfma16(bf16x8 a, bf16x8 b, f32x4 c) { return __builtin_amdgcn_mfma_f32_16x16x32_bf16(a, b, c, 0, 0, 0); }
; __device__ __forceinline__ void attn_unit(LAS unsigned char* lds, const bf16* P, bf16* Y, const float* gq, const float* gk, int b, int h, int qb, int tid, int wid, int lane, ...
;     ...
;                         const int st = 2 * p + u, sg = 8 * kt + st;
;                         if (sg > tg) {
; #pragma unroll
;                             for (int j = 0; j < 4; ++j) av[u][j] = 0.f;
;                         } else {
;                             const bf16x8 a0 = *(const LAS bf16x8*)(Ks + (16 * st + tq) * 72 + 8 * quad), a1 = *(const LAS bf16x8*)(Ks + (16 * st + tq) * 72 + 32 + 8 * quad);
;                             f32x4 z = (f32x4){0.f, 0.f, 0.f, 0.f};
;                             z = mfma16(a0, Bq0, z); z = mfma16(a1, Bq1, z);
;                             float r[4], be[4];
; #pragma unroll
;                             for (int j = 0; j < 4; ++j) { const float e = fexp2(fminf(z[j], 80.f)); const float rr = frcp(1.0f + e); r[j] = rr; be[j] = e * rr; }
;                             if (sg == tg) {
;                                 int tql = tq; asm volatile("" : "+v"(tql));
; #pragma unroll
;                                 for (int j = 0; j < 4; ++j) if (4 * quad + j >= tql) { r[j] = 1.0f; be[j] = 0.f; }
.LBB0_964:
	ds_read_b128 v[60:63], v141
	ds_read_b128 v[64:67], v141 offset:64
	s_cmp_lg_u32 s49, s76
	s_waitcnt lgkmcnt(1)
	v_mfma_f32_16x16x32_bf16 v[60:63], v[60:63], v[24:27], 0
	s_waitcnt lgkmcnt(0)
	v_mfma_f32_16x16x32_bf16 v[60:63], v[64:67], v[28:31], v[60:63]
	s_nop 7
	v_min_f32_e32 v60, 0x42a00000, v60
	v_min_f32_e32 v61, 0x42a00000, v61
	v_min_f32_e32 v64, 0x42a00000, v62
	v_min_f32_e32 v65, 0x42a00000, v63
	v_exp_f32_e32 v62, v60
	v_exp_f32_e32 v63, v61
	v_exp_f32_e32 v84, v64
	v_exp_f32_e32 v85, v65
	v_pk_add_f32 v[60:61], v[62:63], v[250:251]
	v_pk_add_f32 v[64:65], v[84:85], v[250:251]
	v_rcp_f32_e32 v66, v60
	v_rcp_f32_e32 v67, v61
	v_rcp_f32_e32 v60, v64
	v_rcp_f32_e32 v61, v65
	v_pk_mul_f32 v[64:65], v[62:63], v[66:67]
	v_pk_mul_f32 v[62:63], v[84:85], v[60:61]
	s_cbranch_scc1 .LBB0_966
	v_mov_b32_e32 v84, v91
	s_nop 0
	v_cmp_lt_i32_e64 s[12:13], v131, v84
	v_cmp_lt_i32_e64 s[14:15], v132, v84
	v_cmp_lt_i32_e64 s[10:11], v130, v84
	s_or_b64 s[12:13], s[14:15], s[12:13]
	v_cmp_lt_i32_e32 vcc, v98, v84
	s_or_b64 s[10:11], s[12:13], s[10:11]
	s_or_b64 vcc, s[10:11], vcc
	v_cndmask_b32_e64 v63, 0, v63, s[14:15]
	v_cndmask_b32_e64 v62, 0, v62, s[12:13]
	v_cndmask_b32_e64 v65, 0, v65, s[10:11]
	v_cndmask_b32_e32 v64, 0, v64, vcc
	v_cndmask_b32_e64 v60, 1.0, v60, s[12:13]
	v_cndmask_b32_e64 v67, 1.0, v67, s[10:11]
	v_cndmask_b32_e32 v66, 1.0, v66, vcc
	v_cndmask_b32_e64 v61, 1.0, v61, s[14:15]

; #define LAS __attribute__((address_space(3)))
; __device__ __forceinline__ float fexp2(float x) { return __builtin_amdgcn_exp2f(x); }
; __device__ __forceinline__ float frcp(float x) { return __builtin_amdgcn_rcpf(x); }
; __device__ __forceinline__ f32x4 mfma16(bf16x8 a, bf16x8 b, f32x4 c) { return __builtin_amdgcn_mfma_f32_16x16x32_bf16(a, b, c, 0, 0, 0); }
; __device__ __forceinline__ void attn_unit(LAS unsigned char* lds, const bf16* P, bf16* Y, const float* gq, const float* gk, int b, int h, int qb, int tid, int wid, int lane, ...
;     ...
;                         const int st = 2 * p + u, sg = 8 * kt + st;
;                         if (sg > tg) {
; #pragma unroll
;                             for (int j = 0; j < 4; ++j) av[u][j] = 0.f;
;                         } else {
;                             const bf16x8 a0 = *(const LAS bf16x8*)(Ks + (16 * st + tq) * 72 + 8 * quad), a1 = *(const LAS bf16x8*)(Ks + (16 * st + tq) * 72 + 32 + 8 * quad);
;                             f32x4 z = (f32x4){0.f, 0.f, 0.f, 0.f};
;                             z = mfma16(a0, Bq0, z); z = mfma16(a1, Bq1, z);
;                             float r[4], be[4];
; #pragma unroll
;                             for (int j = 0; j < 4; ++j) { const float e = fexp2(fminf(z[j], 80.f)); const float rr = frcp(1.0f + e); r[j] = rr; be[j] = e * rr; }
;                             if (sg == tg) {
;                                 int tql = tq; asm volatile("" : "+v"(tql));
; #pragma unroll
;                                 for (int j = 0; j < 4; ++j) if (4 * quad + j >= tql) { r[j] = 1.0f; be[j] = 0.f; }
.LBB0_973:
	s_addk_i32 s80, 0x70
	s_cmp_gt_u32 s80, s41
	s_cselect_b64 s[12:13], -1, 0
	s_or_b64 s[12:13], s[12:13], s[10:11]
	s_and_b64 vcc, exec, s[12:13]
	s_cbranch_vccnz .LBB0_994
	s_cmp_ge_u32 s80, s41
	v_mov_b32_e32 v59, 0
	s_cbranch_scc1 .LBB0_984
	ds_read_b128 v[56:59], v138 offset:2304
	ds_read_b128 v[60:63], v138 offset:2368
	s_cmp_lg_u32 s3, s76
	s_waitcnt lgkmcnt(1)
	v_mfma_f32_16x16x32_bf16 v[56:59], v[56:59], v[24:27], 0
	s_waitcnt lgkmcnt(0)
	v_mfma_f32_16x16x32_bf16 v[56:59], v[60:63], v[28:31], v[56:59]
	s_nop 7
	v_min_f32_e32 v56, 0x42a00000, v56
	v_min_f32_e32 v57, 0x42a00000, v57
	v_min_f32_e32 v60, 0x42a00000, v58
	v_min_f32_e32 v61, 0x42a00000, v59
	v_exp_f32_e32 v58, v56
	v_exp_f32_e32 v59, v57
	v_exp_f32_e32 v60, v60
	v_exp_f32_e32 v61, v61
	v_pk_add_f32 v[56:57], v[58:59], v[250:251]
	v_pk_add_f32 v[64:65], v[60:61], v[250:251]
	v_rcp_f32_e32 v62, v56
	v_rcp_f32_e32 v63, v57
	v_rcp_f32_e32 v56, v64
	v_rcp_f32_e32 v57, v65
	v_pk_mul_f32 v[58:59], v[58:59], v[62:63]
	v_pk_mul_f32 v[60:61], v[60:61], v[56:57]
	s_cbranch_scc1 .LBB0_977
	v_mov_b32_e32 v64, v91
	s_nop 0
	v_cmp_lt_i32_e64 s[12:13], v131, v64
	v_cmp_lt_i32_e64 s[14:15], v132, v64
	v_cmp_lt_i32_e64 s[10:11], v130, v64
	s_or_b64 s[12:13], s[14:15], s[12:13]
	v_cmp_lt_i32_e32 vcc, v98, v64
	s_or_b64 s[10:11], s[12:13], s[10:11]
	s_or_b64 vcc, s[10:11], vcc
	v_cndmask_b32_e64 v61, 0, v61, s[14:15]
	v_cndmask_b32_e64 v60, 0, v60, s[12:13]
	v_cndmask_b32_e64 v59, 0, v59, s[10:11]
	v_cndmask_b32_e32 v58, 0, v58, vcc
	v_cndmask_b32_e64 v56, 1.0, v56, s[12:13]
	v_cndmask_b32_e64 v63, 1.0, v63, s[10:11]
	v_cndmask_b32_e32 v62, 1.0, v62, vcc
	v_cndmask_b32_e64 v57, 1.0, v57, s[14:15]

; #define LAS __attribute__((address_space(3)))
; __device__ __forceinline__ float fexp2(float x) { return __builtin_amdgcn_exp2f(x); }
; __device__ __forceinline__ float frcp(float x) { return __builtin_amdgcn_rcpf(x); }
; __device__ __forceinline__ f32x4 mfma16(bf16x8 a, bf16x8 b, f32x4 c) { return __builtin_amdgcn_mfma_f32_16x16x32_bf16(a, b, c, 0, 0, 0); }
; __device__ __forceinline__ void attn_unit(LAS unsigned char* lds, const bf16* P, bf16* Y, const float* gq, const float* gk, int b, int h, int qb, int tid, int wid, int lane, ...
;     ...
;                         const int st = 2 * p + u, sg = 8 * kt + st;
;                         if (sg > tg) {
; #pragma unroll
;                             for (int j = 0; j < 4; ++j) av[u][j] = 0.f;
;                         } else {
;                             const bf16x8 a0 = *(const LAS bf16x8*)(Ks + (16 * st + tq) * 72 + 8 * quad), a1 = *(const LAS bf16x8*)(Ks + (16 * st + tq) * 72 + 32 + 8 * quad);
;                             f32x4 z = (f32x4){0.f, 0.f, 0.f, 0.f};
;                             z = mfma16(a0, Bq0, z); z = mfma16(a1, Bq1, z);
;                             float r[4], be[4];
; #pragma unroll
;                             for (int j = 0; j < 4; ++j) { const float e = fexp2(fminf(z[j], 80.f)); const float rr = frcp(1.0f + e); r[j] = rr; be[j] = e * rr; }
;                             if (sg == tg) {
;                                 int tql = tq; asm volatile("" : "+v"(tql));
; #pragma unroll
;                                 for (int j = 0; j < 4; ++j) if (4 * quad + j >= tql) { r[j] = 1.0f; be[j] = 0.f; }
.LBB0_985:
	ds_read_b128 v[60:63], v138
	ds_read_b128 v[64:67], v138 offset:64
	s_cmp_lg_u32 s33, s76
	s_waitcnt lgkmcnt(1)
	v_mfma_f32_16x16x32_bf16 v[60:63], v[60:63], v[24:27], 0
	s_waitcnt lgkmcnt(0)
	v_mfma_f32_16x16x32_bf16 v[60:63], v[64:67], v[28:31], v[60:63]
	s_nop 7
	v_min_f32_e32 v60, 0x42a00000, v60
	v_min_f32_e32 v61, 0x42a00000, v61
	v_min_f32_e32 v64, 0x42a00000, v62
	v_min_f32_e32 v65, 0x42a00000, v63
	v_exp_f32_e32 v62, v60
	v_exp_f32_e32 v63, v61
	v_exp_f32_e32 v84, v64
	v_exp_f32_e32 v85, v65
	v_pk_add_f32 v[60:61], v[62:63], v[250:251]
	v_pk_add_f32 v[64:65], v[84:85], v[250:251]
	v_rcp_f32_e32 v66, v60
	v_rcp_f32_e32 v67, v61
	v_rcp_f32_e32 v60, v64
	v_rcp_f32_e32 v61, v65
	v_pk_mul_f32 v[64:65], v[62:63], v[66:67]
	v_pk_mul_f32 v[62:63], v[84:85], v[60:61]
	s_cbranch_scc1 .LBB0_987
	v_mov_b32_e32 v84, v91
	s_nop 0
	v_cmp_lt_i32_e64 s[12:13], v131, v84
	v_cmp_lt_i32_e64 s[14:15], v132, v84
	v_cmp_lt_i32_e64 s[10:11], v130, v84
	s_or_b64 s[12:13], s[14:15], s[12:13]
	v_cmp_lt_i32_e32 vcc, v98, v84
	s_or_b64 s[10:11], s[12:13], s[10:11]
	s_or_b64 vcc, s[10:11], vcc
	v_cndmask_b32_e64 v63, 0, v63, s[14:15]
	v_cndmask_b32_e64 v62, 0, v62, s[12:13]
	v_cndmask_b32_e64 v65, 0, v65, s[10:11]
	v_cndmask_b32_e32 v64, 0, v64, vcc
	v_cndmask_b32_e64 v60, 1.0, v60, s[12:13]
	v_cndmask_b32_e64 v67, 1.0, v67, s[10:11]
	v_cndmask_b32_e32 v66, 1.0, v66, vcc
	v_cndmask_b32_e64 v61, 1.0, v61, s[14:15]

; #define LAS __attribute__((address_space(3)))
; __global__ void __launch_bounds__(512, 2) hybrid_fwd(Args a) {
;     extern __shared__ __attribute__((aligned(16))) unsigned char lds_raw[];
;     LAS unsigned char* lds = (LAS unsigned char*)lds_raw;
;     const int tid = threadIdx.x, lane = tid & 63, wid = __builtin_amdgcn_readfirstlane(tid >> 6);
	.amdhsa_kernel _Z10hybrid_fwd4Args
		.amdhsa_group_segment_fixed_size 0
		.amdhsa_private_segment_fixed_size 0
		.amdhsa_kernarg_size 416
		.amdhsa_user_sgpr_count 2
		.amdhsa_user_sgpr_dispatch_ptr 0
		.amdhsa_user_sgpr_queue_ptr 0
		.amdhsa_user_sgpr_kernarg_segment_ptr 1
		.amdhsa_user_sgpr_dispatch_id 0
		.amdhsa_user_sgpr_kernarg_preload_length 0
		.amdhsa_user_sgpr_kernarg_preload_offset 0
		.amdhsa_user_sgpr_private_segment_size 0
		.amdhsa_uses_dynamic_stack 0
		.amdhsa_enable_private_segment 0
		.amdhsa_system_sgpr_workgroup_id_x 1
		.amdhsa_system_sgpr_workgroup_id_y 0
		.amdhsa_system_sgpr_workgroup_id_z 0
		.amdhsa_system_sgpr_workgroup_info 0
		.amdhsa_system_vgpr_workitem_id 2
		.amdhsa_next_free_vgpr 252
		.amdhsa_next_free_sgpr 102
		.amdhsa_accum_offset 252
		.amdhsa_reserve_vcc 1
		.amdhsa_float_round_mode_32 0
		.amdhsa_float_round_mode_16_64 0
		.amdhsa_float_denorm_mode_32 3
		.amdhsa_float_denorm_mode_16_64 3
		.amdhsa_dx10_clamp 1
		.amdhsa_ieee_mode 1
		.amdhsa_fp16_overflow 0
		.amdhsa_tg_split 0
		.amdhsa_exception_fp_ieee_invalid_op 0
		.amdhsa_exception_fp_denorm_src 0
		.amdhsa_exception_fp_ieee_div_zero 0
		.amdhsa_exception_fp_ieee_overflow 0
		.amdhsa_exception_fp_ieee_underflow 0
		.amdhsa_exception_fp_ieee_inexact 0
		.amdhsa_exception_int_div_zero 0
	.end_amdhsa_kernel

; __global__ void __launch_bounds__(512, 2) hybrid_fwd(Args a) {
amdhsa.kernels:
  - .agpr_count:     0
    .args:
      - .offset:         0
        .size:           160
        .value_kind:     by_value
      - .offset:         160
        .size:           4
        .value_kind:     hidden_block_count_x
      - .offset:         164
        .size:           4
        .value_kind:     hidden_block_count_y
      - .offset:         168
        .size:           4
        .value_kind:     hidden_block_count_z
      - .offset:         172
        .size:           2
        .value_kind:     hidden_group_size_x
      - .offset:         174
        .size:           2
        .value_kind:     hidden_group_size_y
      - .offset:         176
        .size:           2
        .value_kind:     hidden_group_size_z
      - .offset:         178
        .size:           2
        .value_kind:     hidden_remainder_x
      - .offset:         180
        .size:           2
        .value_kind:     hidden_remainder_y
      - .offset:         182
        .size:           2
        .value_kind:     hidden_remainder_z
      - .offset:         200
        .size:           8
        .value_kind:     hidden_global_offset_x
      - .offset:         208
        .size:           8
        .value_kind:     hidden_global_offset_y
      - .offset:         216
        .size:           8
        .value_kind:     hidden_global_offset_z
      - .offset:         224
        .size:           2
        .value_kind:     hidden_grid_dims
      - .offset:         248
        .size:           8
        .value_kind:     hidden_multigrid_sync_arg
      - .offset:         280
        .size:           4
        .value_kind:     hidden_dynamic_lds_size
    .group_segment_fixed_size: 0
    .kernarg_segment_align: 8
    .kernarg_segment_size: 416
    .language:       OpenCL C
    .language_version:
      - 2
      - 0
    .max_flat_workgroup_size: 512
    .name:           _Z10hybrid_fwd4Args
    .private_segment_fixed_size: 0
    .sgpr_count:     108
    .sgpr_spill_count: 158
    .symbol:         _Z10hybrid_fwd4Args.kd
    .uniform_work_group_size: 1
    .uses_dynamic_stack: false
    .vgpr_count:     252
    .vgpr_spill_count: 0
    .wavefront_size: 64
